# small sample-row GEMM loops: loads hoisted above MFMAs with unique regs, single wait
# speedup vs baseline: 1.0033x; 1.0033x over previous
; __device__ __forceinline__ void wave_bias(const bf16_t* A, const bf16_t* Bt, int N, float* BW, int unit, int lane) {
;     const int fr = lane & 15, fq = lane >> 4;
;     f32x4 a0 = (f32x4){0.f, 0.f, 0.f, 0.f}, a1 = a0;
;     const bf16_t* ap = A + (size_t)fr * 1024 + 8 * fq; const bf16_t* bp = Bt + (size_t)(16 * unit + fr) * 1024 + 8 * fq;
; #pragma unroll 8
;     for (int k = 0; k < 1024; k += 32) { const bf16x8 bv = *(const bf16x8*)(bp + k), x0 = *(const bf16x8*)(ap + k), x1 = *(const bf16x8*)(ap + 16 * 1024 + k);
;         a0 = __builtin_amdgcn_mfma_f32_16x16x32_bf16(bv, x0, a0, 0, 0, 0); a1 = __builtin_amdgcn_mfma_f32_16x16x32_bf16(bv, x1, a1, 0, 0, 0); }
;     *(f32x4*)(BW + (size_t)fr * N + 16 * unit + 4 * fq) = a0;
;     if (fr < 8) *(f32x4*)(BW + (size_t)(16 + fr) * N + 16 * unit + 4 * fq) = a1;
; }
; __global__ void __launch_bounds__(512, 2) fwd_kernel(Params P) {
;     ...
;         for (int un = gw; un < 848; un += NGW) {
;             int r = un;
;             if (r < 704) { const int mi = r / 352, inst = mi == 0 ? 0 : 2; wave_bias(SHB + (size_t)inst * 128 * 1024, WFI + (size_t)mi * 5632 * 1024, 5632, BW + (size_t)mi * 24 * 5632, r % 352, lane); continue; } r -= 704;
;             wave_bias(SHB + (size_t)1 * 128 * 1024, WABI, 2304, BWAB, r, lane);
;         }
.LBB0_191:
	v_lshl_add_u64 v[26:27], v[22:23], 0, v[168:169]
	v_add_co_u32_e32 v54, vcc, 0x43b0000, v26
	v_lshl_add_u64 v[38:39], v[24:25], 0, v[168:169]
	s_nop 0
	v_addc_co_u32_e32 v55, vcc, 0, v27, vcc
	global_load_dwordx4 v[72:75], v[54:55], off
	v_add_co_u32_e32 v58, vcc, 0x1e378000, v38
	s_addk_i32 s4, 0x100
	s_nop 0
	v_addc_co_u32_e32 v59, vcc, 0, v39, vcc
	global_load_dwordx4 v[76:79], v[54:55], off offset:64
	global_load_dwordx4 v[82:85], v[58:59], off
	v_add_co_u32_e32 v60, vcc, 0x1e380000, v38
	v_lshl_add_u64 v[24:25], v[24:25], 0, s[6:7]
	s_nop 0
	v_addc_co_u32_e32 v61, vcc, 0, v39, vcc
	global_load_dwordx4 v[86:89], v[58:59], off offset:64
	global_load_dwordx4 v[90:93], v[60:61], off
	s_cmpk_gt_u32 s4, 0x3df
	v_lshl_add_u64 v[22:23], v[22:23], 0, s[6:7]
	global_load_dwordx4 v[94:97], v[60:61], off offset:64
	global_load_dwordx4 v[104:107], v[54:55], off offset:128
	global_load_dwordx4 v[108:111], v[54:55], off offset:192
	global_load_dwordx4 v[112:115], v[54:55], off offset:256
	global_load_dwordx4 v[116:119], v[58:59], off offset:128
	global_load_dwordx4 v[120:123], v[58:59], off offset:192
	global_load_dwordx4 v[124:127], v[60:61], off offset:128
	global_load_dwordx4 v[128:131], v[60:61], off offset:192
	global_load_dwordx4 v[144:147], v[54:55], off offset:320
	global_load_dwordx4 v[150:153], v[54:55], off offset:384
	global_load_dwordx4 v[154:157], v[54:55], off offset:448
	global_load_dwordx4 v[162:165], v[58:59], off offset:256
	s_nop 0
	global_load_dwordx4 v[172:175], v[58:59], off offset:320
	global_load_dwordx4 v[182:185], v[60:61], off offset:256
	global_load_dwordx4 v[186:189], v[60:61], off offset:320
	global_load_dwordx4 v[190:193], v[58:59], off offset:384
	global_load_dwordx4 v[194:197], v[60:61], off offset:384
	global_load_dwordx4 v[198:201], v[58:59], off offset:448
	global_load_dwordx4 v[202:205], v[60:61], off offset:448
	s_waitcnt vmcnt(0)
	v_mfma_f32_16x16x32_bf16 v[0:3], v[72:75], v[82:85], v[0:3]
	v_mfma_f32_16x16x32_bf16 v[4:7], v[72:75], v[90:93], v[4:7]
	v_mfma_f32_16x16x32_bf16 v[0:3], v[76:79], v[86:89], v[0:3]
	v_mfma_f32_16x16x32_bf16 v[4:7], v[76:79], v[94:97], v[4:7]
	v_mfma_f32_16x16x32_bf16 v[0:3], v[104:107], v[116:119], v[0:3]
	v_mfma_f32_16x16x32_bf16 v[0:3], v[108:111], v[120:123], v[0:3]
	v_mfma_f32_16x16x32_bf16 v[4:7], v[104:107], v[124:127], v[4:7]
	v_mfma_f32_16x16x32_bf16 v[4:7], v[108:111], v[128:131], v[4:7]
	v_mfma_f32_16x16x32_bf16 v[0:3], v[112:115], v[162:165], v[0:3]
	v_mfma_f32_16x16x32_bf16 v[4:7], v[112:115], v[182:185], v[4:7]
	v_mfma_f32_16x16x32_bf16 v[0:3], v[144:147], v[172:175], v[0:3]
	v_mfma_f32_16x16x32_bf16 v[4:7], v[144:147], v[186:189], v[4:7]
	v_mfma_f32_16x16x32_bf16 v[0:3], v[150:153], v[190:193], v[0:3]
	v_mfma_f32_16x16x32_bf16 v[4:7], v[150:153], v[194:197], v[4:7]
	v_mfma_f32_16x16x32_bf16 v[0:3], v[154:157], v[198:201], v[0:3]
	v_mfma_f32_16x16x32_bf16 v[4:7], v[154:157], v[202:205], v[4:7]
	s_cbranch_scc0 .LBB0_191
	s_lshl_b32 s4, s23, 4
	s_addk_i32 s4, 0xd400
	v_lshl_add_u64 v[22:23], s[4:5], 2, v[12:13]
	s_nop 1
	global_store_dwordx4 v[22:23], v[0:3], off
	s_and_saveexec_b64 s[10:11], s[0:1]
	s_cbranch_execz .LBB0_194
	v_lshl_add_u64 v[0:1], s[4:5], 2, v[14:15]
	global_store_dwordx4 v[0:1], v[4:7], off

; __device__ __forceinline__ void wave_bias(const bf16_t* A, const bf16_t* Bt, int N, float* BW, int unit, int lane) {
;     const int fr = lane & 15, fq = lane >> 4;
;     f32x4 a0 = (f32x4){0.f, 0.f, 0.f, 0.f}, a1 = a0;
;     const bf16_t* ap = A + (size_t)fr * 1024 + 8 * fq; const bf16_t* bp = Bt + (size_t)(16 * unit + fr) * 1024 + 8 * fq;
; #pragma unroll 8
;     for (int k = 0; k < 1024; k += 32) { const bf16x8 bv = *(const bf16x8*)(bp + k), x0 = *(const bf16x8*)(ap + k), x1 = *(const bf16x8*)(ap + 16 * 1024 + k);
;         a0 = __builtin_amdgcn_mfma_f32_16x16x32_bf16(bv, x0, a0, 0, 0, 0); a1 = __builtin_amdgcn_mfma_f32_16x16x32_bf16(bv, x1, a1, 0, 0, 0); }
;     *(f32x4*)(BW + (size_t)fr * N + 16 * unit + 4 * fq) = a0;
;     if (fr < 8) *(f32x4*)(BW + (size_t)(16 + fr) * N + 16 * unit + 4 * fq) = a1;
; }
; __global__ void __launch_bounds__(512, 2) fwd_kernel(Params P) {
;     ...
;         for (int un = gw; un < 848; un += NGW) {
;             int r = un;
;             if (r < 704) { const int mi = r / 352, inst = mi == 0 ? 0 : 2; wave_bias(SHB + (size_t)inst * 128 * 1024, WFI + (size_t)mi * 5632 * 1024, 5632, BW + (size_t)mi * 24 * 5632, r % 352, lane); continue; } r -= 704;
;             wave_bias(SHB + (size_t)1 * 128 * 1024, WABI, 2304, BWAB, r, lane);
;         }
.LBB0_196:
	v_lshl_add_u64 v[38:39], v[22:23], 0, v[168:169]
	v_add_co_u32_e32 v58, vcc, s17, v38
	v_lshl_add_u64 v[54:55], v[24:25], 0, v[168:169]
	s_nop 0
	v_addc_co_u32_e32 v59, vcc, 0, v39, vcc
	global_load_dwordx4 v[72:75], v[54:55], off offset:-256
	global_load_dwordx4 v[76:79], v[54:55], off offset:-192
	global_load_dwordx4 v[82:85], v[58:59], off
	v_add_co_u32_e32 v60, vcc, s22, v38
	s_addk_i32 s4, 0x100
	s_nop 0
	v_addc_co_u32_e32 v61, vcc, 0, v39, vcc
	global_load_dwordx4 v[86:89], v[58:59], off offset:64
	global_load_dwordx4 v[90:93], v[60:61], off
	v_lshl_add_u64 v[22:23], v[22:23], 0, s[6:7]
	s_cmpk_gt_u32 s4, 0x3df
	v_lshl_add_u64 v[24:25], v[24:25], 0, s[6:7]
	global_load_dwordx4 v[94:97], v[60:61], off offset:64
	global_load_dwordx4 v[104:107], v[54:55], off offset:-128
	global_load_dwordx4 v[108:111], v[54:55], off offset:-64
	global_load_dwordx4 v[112:115], v[54:55], off
	global_load_dwordx4 v[116:119], v[58:59], off offset:128
	global_load_dwordx4 v[120:123], v[58:59], off offset:192
	global_load_dwordx4 v[124:127], v[60:61], off offset:128
	global_load_dwordx4 v[128:131], v[60:61], off offset:192
	global_load_dwordx4 v[144:147], v[54:55], off offset:64
	global_load_dwordx4 v[150:153], v[54:55], off offset:128
	global_load_dwordx4 v[154:157], v[54:55], off offset:192
	global_load_dwordx4 v[162:165], v[58:59], off offset:256
	s_nop 0
	global_load_dwordx4 v[172:175], v[58:59], off offset:320
	global_load_dwordx4 v[182:185], v[60:61], off offset:256
	global_load_dwordx4 v[186:189], v[60:61], off offset:320
	global_load_dwordx4 v[190:193], v[58:59], off offset:384
	global_load_dwordx4 v[194:197], v[60:61], off offset:384
	global_load_dwordx4 v[198:201], v[58:59], off offset:448
	global_load_dwordx4 v[202:205], v[60:61], off offset:448
	s_waitcnt vmcnt(0)
	v_mfma_f32_16x16x32_bf16 v[0:3], v[72:75], v[82:85], v[0:3]
	v_mfma_f32_16x16x32_bf16 v[4:7], v[72:75], v[90:93], v[4:7]
	v_mfma_f32_16x16x32_bf16 v[0:3], v[76:79], v[86:89], v[0:3]
	v_mfma_f32_16x16x32_bf16 v[4:7], v[76:79], v[94:97], v[4:7]
	v_mfma_f32_16x16x32_bf16 v[0:3], v[104:107], v[116:119], v[0:3]
	v_mfma_f32_16x16x32_bf16 v[0:3], v[108:111], v[120:123], v[0:3]
	v_mfma_f32_16x16x32_bf16 v[4:7], v[104:107], v[124:127], v[4:7]
	v_mfma_f32_16x16x32_bf16 v[4:7], v[108:111], v[128:131], v[4:7]
	v_mfma_f32_16x16x32_bf16 v[0:3], v[112:115], v[162:165], v[0:3]
	v_mfma_f32_16x16x32_bf16 v[4:7], v[112:115], v[182:185], v[4:7]
	v_mfma_f32_16x16x32_bf16 v[0:3], v[144:147], v[172:175], v[0:3]
	v_mfma_f32_16x16x32_bf16 v[4:7], v[144:147], v[186:189], v[4:7]
	v_mfma_f32_16x16x32_bf16 v[0:3], v[150:153], v[190:193], v[0:3]
	v_mfma_f32_16x16x32_bf16 v[4:7], v[150:153], v[194:197], v[4:7]
	v_mfma_f32_16x16x32_bf16 v[0:3], v[154:157], v[198:201], v[0:3]
	v_mfma_f32_16x16x32_bf16 v[4:7], v[154:157], v[202:205], v[4:7]
	s_cbranch_scc0 .LBB0_196
	v_mad_i64_i32 v[22:23], s[20:21], s11, v11, v[16:17]
	s_ashr_i32 s11, s10, 31
	v_lshl_add_u64 v[22:23], s[10:11], 2, v[22:23]
	v_lshlrev_b32_e32 v8, 2, v10
	v_lshl_add_u64 v[22:23], v[22:23], 0, v[8:9]
	global_store_dwordx4 v[22:23], v[0:3], off
	s_and_saveexec_b64 s[10:11], s[0:1]
	s_cbranch_execz .LBB0_186
	v_add_co_u32_e32 v0, vcc, 0x58000, v22
	s_nop 1
	v_addc_co_u32_e32 v1, vcc, 0, v23, vcc
	global_store_dwordx4 v[0:1], v[4:7], off
	s_branch .LBB0_186

; template <int NB>
; __device__ __forceinline__ void small_core(LAS unsigned char* lds, const bf16_t* A, int lda, const bf16_t* B0, const bf16_t* B1, int K, f32x4 (&out)[NB]) {
;     ...
;     for (; st + 8 < nsteps; st += 16) {
;         const int k = st * 32, k2 = k + 256;
;         bf16x8 b[NB], b2[NB]; b[0] = *(const bf16x8*)(bp0 + k); b2[0] = *(const bf16x8*)(bp0 + k2);
;         if (NB == 2) { b[NB - 1] = *(const bf16x8*)(bp1 + k); b2[NB - 1] = *(const bf16x8*)(bp1 + k2); }
;         bf16x8 a[8], a2[8];
; #pragma unroll
;         for (int mb = 0; mb < 8; ++mb) { a[mb] = *(const bf16x8*)(ap + (size_t)(16 * mb) * lda + k); a2[mb] = *(const bf16x8*)(ap + (size_t)(16 * mb) * lda + k2); }
; #pragma unroll
;         for (int mb = 0; mb < 8; ++mb)
; #pragma unroll
;             for (int nb = 0; nb < NB; ++nb) { acc[nb][mb] = __builtin_amdgcn_mfma_f32_16x16x32_bf16(b[nb], a[mb], acc[nb][mb], 0, 0, 0);
;                 acc[nb][mb] = __builtin_amdgcn_mfma_f32_16x16x32_bf16(b2[nb], a2[mb], acc[nb][mb], 0, 0, 0); }
;     }
.LBB0_256:
	s_ashr_i32 s53, s52, 31
	s_lshl_b64 s[20:21], s[52:53], 1
	v_lshl_add_u64 v[106:107], v[78:79], 0, s[20:21]
	v_lshl_add_u64 v[118:119], v[80:81], 0, s[20:21]
	v_lshl_add_u64 v[110:111], v[76:77], 0, s[20:21]
	global_load_dwordx4 v[152:155], v[106:107], off
	global_load_dwordx4 v[156:159], v[110:111], off
	s_nop 0
	global_load_dwordx4 v[162:165], v[106:107], off offset:512
	s_nop 0
	global_load_dwordx4 v[172:175], v[110:111], off offset:512
	s_nop 0
	global_load_dwordx4 v[182:185], v[118:119], off
	s_nop 0
	global_load_dwordx4 v[186:189], v[118:119], off offset:512
	v_lshl_add_u64 v[122:123], v[2:3], 0, s[20:21]
	v_lshl_add_u64 v[126:127], v[82:83], 0, s[20:21]
	v_lshl_add_u64 v[130:131], v[84:85], 0, s[20:21]
	v_lshl_add_u64 v[134:135], v[86:87], 0, s[20:21]
	v_lshl_add_u64 v[138:139], v[88:89], 0, s[20:21]
	v_lshl_add_u64 v[142:143], v[90:91], 0, s[20:21]
	v_lshl_add_u64 v[150:151], v[92:93], 0, s[20:21]
	s_mov_b32 s20, s0
	s_add_i32 s0, s0, 16
	s_addk_i32 s52, 0x200
	s_cmp_lt_i32 s20, 8
	global_load_dwordx4 v[190:193], v[122:123], off
	s_nop 0
	global_load_dwordx4 v[194:197], v[122:123], off offset:512
	global_load_dwordx4 v[198:201], v[126:127], off
	s_nop 0
	global_load_dwordx4 v[202:205], v[126:127], off offset:512
	global_load_dwordx4 v[206:209], v[130:131], off
	s_nop 0
	global_load_dwordx4 v[210:213], v[130:131], off offset:512
	global_load_dwordx4 v[214:217], v[134:135], off
	s_nop 0
	global_load_dwordx4 v[218:221], v[134:135], off offset:512
	global_load_dwordx4 v[222:225], v[138:139], off
	s_nop 0
	global_load_dwordx4 v[226:229], v[138:139], off offset:512
	global_load_dwordx4 v[230:233], v[142:143], off
	s_nop 0
	global_load_dwordx4 v[240:243], v[142:143], off offset:512
	s_nop 0
	global_load_dwordx4 v[246:249], v[150:151], off
	global_load_dwordx4 v[98:101], v[150:151], off offset:512
	s_waitcnt vmcnt(0)
	v_mfma_f32_16x16x32_bf16 v[44:47], v[152:155], v[156:159], v[44:47]
	v_mfma_f32_16x16x32_bf16 v[64:67], v[182:185], v[156:159], v[64:67]
	v_mfma_f32_16x16x32_bf16 v[44:47], v[162:165], v[172:175], v[44:47]
	v_mfma_f32_16x16x32_bf16 v[64:67], v[186:189], v[172:175], v[64:67]
	v_mfma_f32_16x16x32_bf16 v[40:43], v[152:155], v[190:193], v[40:43]
	v_mfma_f32_16x16x32_bf16 v[60:63], v[182:185], v[190:193], v[60:63]
	v_mfma_f32_16x16x32_bf16 v[40:43], v[162:165], v[194:197], v[40:43]
	v_mfma_f32_16x16x32_bf16 v[60:63], v[186:189], v[194:197], v[60:63]
	v_mfma_f32_16x16x32_bf16 v[36:39], v[152:155], v[198:201], v[36:39]
	v_mfma_f32_16x16x32_bf16 v[56:59], v[182:185], v[198:201], v[56:59]
	v_mfma_f32_16x16x32_bf16 v[36:39], v[162:165], v[202:205], v[36:39]
	v_mfma_f32_16x16x32_bf16 v[56:59], v[186:189], v[202:205], v[56:59]
	v_mfma_f32_16x16x32_bf16 v[32:35], v[152:155], v[206:209], v[32:35]
	v_mfma_f32_16x16x32_bf16 v[52:55], v[182:185], v[206:209], v[52:55]
	v_mfma_f32_16x16x32_bf16 v[32:35], v[162:165], v[210:213], v[32:35]
	v_mfma_f32_16x16x32_bf16 v[52:55], v[186:189], v[210:213], v[52:55]
	v_mfma_f32_16x16x32_bf16 v[16:19], v[152:155], v[214:217], v[16:19]
	v_mfma_f32_16x16x32_bf16 v[48:51], v[182:185], v[214:217], v[48:51]
	v_mfma_f32_16x16x32_bf16 v[16:19], v[162:165], v[218:221], v[16:19]
	v_mfma_f32_16x16x32_bf16 v[48:51], v[186:189], v[218:221], v[48:51]
	v_mfma_f32_16x16x32_bf16 v[12:15], v[152:155], v[222:225], v[12:15]
	v_mfma_f32_16x16x32_bf16 v[24:27], v[182:185], v[222:225], v[24:27]
	v_mfma_f32_16x16x32_bf16 v[12:15], v[162:165], v[226:229], v[12:15]
	v_mfma_f32_16x16x32_bf16 v[24:27], v[186:189], v[226:229], v[24:27]
	v_mfma_f32_16x16x32_bf16 v[8:11], v[152:155], v[230:233], v[8:11]
	v_mfma_f32_16x16x32_bf16 v[20:23], v[182:185], v[230:233], v[20:23]
	v_mfma_f32_16x16x32_bf16 v[4:7], v[152:155], v[246:249], v[4:7]
	v_mfma_f32_16x16x32_bf16 v[28:31], v[182:185], v[246:249], v[28:31]
	v_mfma_f32_16x16x32_bf16 v[8:11], v[162:165], v[240:243], v[8:11]
	v_mfma_f32_16x16x32_bf16 v[20:23], v[186:189], v[240:243], v[20:23]
	v_mfma_f32_16x16x32_bf16 v[4:7], v[162:165], v[98:101], v[4:7]
	v_mfma_f32_16x16x32_bf16 v[28:31], v[186:189], v[98:101], v[28:31]
	s_cbranch_scc1 .LBB0_256

; template <int NB>
; __device__ __forceinline__ void small_core(LAS unsigned char* lds, const bf16_t* A, int lda, const bf16_t* B0, const bf16_t* B1, int K, f32x4 (&out)[NB]) {
;     ...
;     for (; st + 8 < nsteps; st += 16) {
;         const int k = st * 32, k2 = k + 256;
;         bf16x8 b[NB], b2[NB]; b[0] = *(const bf16x8*)(bp0 + k); b2[0] = *(const bf16x8*)(bp0 + k2);
;         if (NB == 2) { b[NB - 1] = *(const bf16x8*)(bp1 + k); b2[NB - 1] = *(const bf16x8*)(bp1 + k2); }
;         bf16x8 a[8], a2[8];
; #pragma unroll
;         for (int mb = 0; mb < 8; ++mb) { a[mb] = *(const bf16x8*)(ap + (size_t)(16 * mb) * lda + k); a2[mb] = *(const bf16x8*)(ap + (size_t)(16 * mb) * lda + k2); }
; #pragma unroll
;         for (int mb = 0; mb < 8; ++mb)
; #pragma unroll
;             for (int nb = 0; nb < NB; ++nb) { acc[nb][mb] = __builtin_amdgcn_mfma_f32_16x16x32_bf16(b[nb], a[mb], acc[nb][mb], 0, 0, 0);
;                 acc[nb][mb] = __builtin_amdgcn_mfma_f32_16x16x32_bf16(b2[nb], a2[mb], acc[nb][mb], 0, 0, 0); }
;     }
;     if (st < nsteps) {
;         const int k = st * 32;
;         bf16x8 b[NB]; b[0] = *(const bf16x8*)(bp0 + k); if (NB == 2) b[NB - 1] = *(const bf16x8*)(bp1 + k);
;         bf16x8 a[8];
; #pragma unroll
;         for (int mb = 0; mb < 8; ++mb) a[mb] = *(const bf16x8*)(ap + (size_t)(16 * mb) * lda + k);
; #pragma unroll
;         for (int mb = 0; mb < 8; ++mb)
; #pragma unroll
;             for (int nb = 0; nb < NB; ++nb) acc[nb][mb] = __builtin_amdgcn_mfma_f32_16x16x32_bf16(b[nb], a[mb], acc[nb][mb], 0, 0, 0);
;     }
.LBB0_332:
	s_ashr_i32 s11, s10, 31
	s_lshl_b64 s[20:21], s[10:11], 1
	v_lshl_add_u64 v[80:81], v[48:49], 0, s[20:21]
	v_lshl_add_u64 v[82:83], v[46:47], 0, s[20:21]
	v_lshl_add_u64 v[84:85], v[50:51], 0, s[20:21]
	global_load_dwordx4 v[104:107], v[80:81], off
	global_load_dwordx4 v[108:111], v[82:83], off
	global_load_dwordx4 v[112:115], v[84:85], off
	v_lshl_add_u64 v[86:87], v[52:53], 0, s[20:21]
	v_lshl_add_u64 v[88:89], v[54:55], 0, s[20:21]
	v_lshl_add_u64 v[90:91], v[56:57], 0, s[20:21]
	v_lshl_add_u64 v[92:93], v[58:59], 0, s[20:21]
	v_lshl_add_u64 v[94:95], v[60:61], 0, s[20:21]
	v_lshl_add_u64 v[96:97], v[62:63], 0, s[20:21]
	s_mov_b32 s11, s4
	s_add_i32 s4, s4, 16
	s_addk_i32 s10, 0x200
	s_cmp_lt_i32 s11, 64
	global_load_dwordx4 v[116:119], v[86:87], off
	global_load_dwordx4 v[120:123], v[88:89], off
	global_load_dwordx4 v[124:127], v[90:91], off
	global_load_dwordx4 v[128:131], v[92:93], off
	global_load_dwordx4 v[144:147], v[94:95], off
	global_load_dwordx4 v[150:153], v[96:97], off
	global_load_dwordx4 v[154:157], v[80:81], off offset:512
	global_load_dwordx4 v[162:165], v[82:83], off offset:512
	global_load_dwordx4 v[172:175], v[84:85], off offset:512
	global_load_dwordx4 v[182:185], v[86:87], off offset:512
	global_load_dwordx4 v[186:189], v[88:89], off offset:512
	global_load_dwordx4 v[190:193], v[90:91], off offset:512
	global_load_dwordx4 v[194:197], v[92:93], off offset:512
	global_load_dwordx4 v[198:201], v[94:95], off offset:512
	global_load_dwordx4 v[202:205], v[96:97], off offset:512
	s_waitcnt vmcnt(0)
	v_mfma_f32_16x16x32_bf16 v[28:31], v[104:107], v[108:111], v[28:31]
	v_mfma_f32_16x16x32_bf16 v[24:27], v[104:107], v[112:115], v[24:27]
	v_mfma_f32_16x16x32_bf16 v[20:23], v[104:107], v[116:119], v[20:23]
	v_mfma_f32_16x16x32_bf16 v[16:19], v[104:107], v[120:123], v[16:19]
	v_mfma_f32_16x16x32_bf16 v[12:15], v[104:107], v[124:127], v[12:15]
	v_mfma_f32_16x16x32_bf16 v[4:7], v[104:107], v[128:131], v[4:7]
	v_mfma_f32_16x16x32_bf16 v[0:3], v[104:107], v[144:147], v[0:3]
	v_mfma_f32_16x16x32_bf16 v[8:11], v[104:107], v[150:153], v[8:11]
	v_mfma_f32_16x16x32_bf16 v[28:31], v[154:157], v[162:165], v[28:31]
	v_mfma_f32_16x16x32_bf16 v[24:27], v[154:157], v[172:175], v[24:27]
	v_mfma_f32_16x16x32_bf16 v[20:23], v[154:157], v[182:185], v[20:23]
	v_mfma_f32_16x16x32_bf16 v[16:19], v[154:157], v[186:189], v[16:19]
	v_mfma_f32_16x16x32_bf16 v[12:15], v[154:157], v[190:193], v[12:15]
	v_mfma_f32_16x16x32_bf16 v[4:7], v[154:157], v[194:197], v[4:7]
	v_mfma_f32_16x16x32_bf16 v[0:3], v[154:157], v[198:201], v[0:3]
	v_mfma_f32_16x16x32_bf16 v[8:11], v[154:157], v[202:205], v[8:11]
	s_cbranch_scc1 .LBB0_332
.LBB0_333:
	s_cmpk_gt_u32 s4, 0x57
	s_cbranch_scc1 .LBB0_335
	s_lshl_b32 s4, s4, 6
	v_lshl_add_u64 v[48:49], v[48:49], 0, s[4:5]
	global_load_dwordx4 v[104:107], v[48:49], off
	v_lshl_add_u64 v[46:47], v[46:47], 0, s[4:5]
	global_load_dwordx4 v[108:111], v[46:47], off
	v_add_co_u32_e32 v56, vcc, 0x16000, v46
	v_addc_co_u32_e32 v57, vcc, 0, v47, vcc
	v_add_co_u32_e32 v60, vcc, 0x2c000, v46
	s_nop 1
	v_addc_co_u32_e32 v61, vcc, 0, v47, vcc
	v_add_co_u32_e32 v68, vcc, 0x42000, v46
	global_load_dwordx4 v[112:115], v[56:57], off
	s_nop 0
	global_load_dwordx4 v[116:119], v[60:61], off
	v_addc_co_u32_e32 v69, vcc, 0, v47, vcc
	v_add_co_u32_e32 v72, vcc, 0x58000, v46
	v_addc_co_u32_e32 v73, vcc, 0, v47, vcc
	global_load_dwordx4 v[120:123], v[72:73], off
	v_add_co_u32_e32 v72, vcc, 0x6e000, v46
	s_nop 0
	v_addc_co_u32_e32 v73, vcc, 0, v47, vcc
	v_add_co_u32_e32 v60, vcc, 0x84000, v46
	global_load_dwordx4 v[124:127], v[72:73], off
	s_nop 0
	v_addc_co_u32_e32 v61, vcc, 0, v47, vcc
	global_load_dwordx4 v[128:131], v[60:61], off
	v_add_co_u32_e32 v46, vcc, 0x9a000, v46
	global_load_dwordx4 v[144:147], v[68:69], off
	s_nop 0
	v_addc_co_u32_e32 v47, vcc, 0, v47, vcc
	global_load_dwordx4 v[150:153], v[46:47], off
	s_waitcnt vmcnt(0)
	v_mfma_f32_16x16x32_bf16 v[28:31], v[104:107], v[108:111], v[28:31]
	v_mfma_f32_16x16x32_bf16 v[20:23], v[104:107], v[116:119], v[20:23]
	v_mfma_f32_16x16x32_bf16 v[24:27], v[104:107], v[112:115], v[24:27]
	v_mfma_f32_16x16x32_bf16 v[12:15], v[104:107], v[120:123], v[12:15]
	v_mfma_f32_16x16x32_bf16 v[0:3], v[104:107], v[128:131], v[0:3]
	v_mfma_f32_16x16x32_bf16 v[16:19], v[104:107], v[144:147], v[16:19]
	v_mfma_f32_16x16x32_bf16 v[4:7], v[104:107], v[124:127], v[4:7]
	v_mfma_f32_16x16x32_bf16 v[8:11], v[104:107], v[150:153], v[8:11]

; template <int NB>
; __device__ __forceinline__ void small_core(LAS unsigned char* lds, const bf16_t* A, int lda, const bf16_t* B0, const bf16_t* B1, int K, f32x4 (&out)[NB]) {
;     ...
;     for (; st + 8 < nsteps; st += 16) {
;         const int k = st * 32, k2 = k + 256;
;         bf16x8 b[NB], b2[NB]; b[0] = *(const bf16x8*)(bp0 + k); b2[0] = *(const bf16x8*)(bp0 + k2);
;         if (NB == 2) { b[NB - 1] = *(const bf16x8*)(bp1 + k); b2[NB - 1] = *(const bf16x8*)(bp1 + k2); }
;         bf16x8 a[8], a2[8];
; #pragma unroll
;         for (int mb = 0; mb < 8; ++mb) { a[mb] = *(const bf16x8*)(ap + (size_t)(16 * mb) * lda + k); a2[mb] = *(const bf16x8*)(ap + (size_t)(16 * mb) * lda + k2); }
; #pragma unroll
;         for (int mb = 0; mb < 8; ++mb)
; #pragma unroll
;             for (int nb = 0; nb < NB; ++nb) { acc[nb][mb] = __builtin_amdgcn_mfma_f32_16x16x32_bf16(b[nb], a[mb], acc[nb][mb], 0, 0, 0);
;                 acc[nb][mb] = __builtin_amdgcn_mfma_f32_16x16x32_bf16(b2[nb], a2[mb], acc[nb][mb], 0, 0, 0); }
;     }
.LBB0_440:
	s_ashr_i32 s13, s12, 31
	s_lshl_b64 s[20:21], s[12:13], 1
	v_lshl_add_u64 v[76:77], v[44:45], 0, s[20:21]
	v_lshl_add_u64 v[78:79], v[42:43], 0, s[20:21]
	v_lshl_add_u64 v[80:81], v[46:47], 0, s[20:21]
	global_load_dwordx4 v[94:97], v[76:77], off
	global_load_dwordx4 v[104:107], v[78:79], off
	global_load_dwordx4 v[108:111], v[80:81], off
	v_lshl_add_u64 v[82:83], v[48:49], 0, s[20:21]
	v_lshl_add_u64 v[84:85], v[50:51], 0, s[20:21]
	v_lshl_add_u64 v[86:87], v[52:53], 0, s[20:21]
	v_lshl_add_u64 v[88:89], v[54:55], 0, s[20:21]
	v_lshl_add_u64 v[90:91], v[56:57], 0, s[20:21]
	v_lshl_add_u64 v[92:93], v[58:59], 0, s[20:21]
	s_mov_b32 s13, s0
	s_add_i32 s0, s0, 16
	s_addk_i32 s12, 0x200
	s_cmp_lt_i32 s13, 8
	global_load_dwordx4 v[112:115], v[82:83], off
	global_load_dwordx4 v[116:119], v[84:85], off
	global_load_dwordx4 v[120:123], v[86:87], off
	global_load_dwordx4 v[124:127], v[88:89], off
	global_load_dwordx4 v[128:131], v[90:91], off
	global_load_dwordx4 v[144:147], v[92:93], off
	global_load_dwordx4 v[150:153], v[76:77], off offset:512
	global_load_dwordx4 v[154:157], v[78:79], off offset:512
	global_load_dwordx4 v[162:165], v[80:81], off offset:512
	global_load_dwordx4 v[172:175], v[82:83], off offset:512
	global_load_dwordx4 v[182:185], v[84:85], off offset:512
	global_load_dwordx4 v[186:189], v[86:87], off offset:512
	global_load_dwordx4 v[190:193], v[88:89], off offset:512
	global_load_dwordx4 v[194:197], v[90:91], off offset:512
	global_load_dwordx4 v[198:201], v[92:93], off offset:512
	s_waitcnt vmcnt(0)
	v_mfma_f32_16x16x32_bf16 v[28:31], v[94:97], v[104:107], v[28:31]
	v_mfma_f32_16x16x32_bf16 v[24:27], v[94:97], v[108:111], v[24:27]
	v_mfma_f32_16x16x32_bf16 v[20:23], v[94:97], v[112:115], v[20:23]
	v_mfma_f32_16x16x32_bf16 v[16:19], v[94:97], v[116:119], v[16:19]
	v_mfma_f32_16x16x32_bf16 v[12:15], v[94:97], v[120:123], v[12:15]
	v_mfma_f32_16x16x32_bf16 v[4:7], v[94:97], v[124:127], v[4:7]
	v_mfma_f32_16x16x32_bf16 v[0:3], v[94:97], v[128:131], v[0:3]
	v_mfma_f32_16x16x32_bf16 v[8:11], v[94:97], v[144:147], v[8:11]
	v_mfma_f32_16x16x32_bf16 v[28:31], v[150:153], v[154:157], v[28:31]
	v_mfma_f32_16x16x32_bf16 v[24:27], v[150:153], v[162:165], v[24:27]
	v_mfma_f32_16x16x32_bf16 v[20:23], v[150:153], v[172:175], v[20:23]
	v_mfma_f32_16x16x32_bf16 v[16:19], v[150:153], v[182:185], v[16:19]
	v_mfma_f32_16x16x32_bf16 v[12:15], v[150:153], v[186:189], v[12:15]
	v_mfma_f32_16x16x32_bf16 v[4:7], v[150:153], v[190:193], v[4:7]
	v_mfma_f32_16x16x32_bf16 v[0:3], v[150:153], v[194:197], v[0:3]
	v_mfma_f32_16x16x32_bf16 v[8:11], v[150:153], v[198:201], v[8:11]
	s_cbranch_scc1 .LBB0_440

; template <int NB>
; __device__ __forceinline__ void small_core(LAS unsigned char* lds, const bf16_t* A, int lda, const bf16_t* B0, const bf16_t* B1, int K, f32x4 (&out)[NB]) {
;     ...
;     for (; st + 8 < nsteps; st += 16) {
;         const int k = st * 32, k2 = k + 256;
;         bf16x8 b[NB], b2[NB]; b[0] = *(const bf16x8*)(bp0 + k); b2[0] = *(const bf16x8*)(bp0 + k2);
;         if (NB == 2) { b[NB - 1] = *(const bf16x8*)(bp1 + k); b2[NB - 1] = *(const bf16x8*)(bp1 + k2); }
;         bf16x8 a[8], a2[8];
; #pragma unroll
;         for (int mb = 0; mb < 8; ++mb) { a[mb] = *(const bf16x8*)(ap + (size_t)(16 * mb) * lda + k); a2[mb] = *(const bf16x8*)(ap + (size_t)(16 * mb) * lda + k2); }
; #pragma unroll
;         for (int mb = 0; mb < 8; ++mb)
; #pragma unroll
;             for (int nb = 0; nb < NB; ++nb) { acc[nb][mb] = __builtin_amdgcn_mfma_f32_16x16x32_bf16(b[nb], a[mb], acc[nb][mb], 0, 0, 0);
;                 acc[nb][mb] = __builtin_amdgcn_mfma_f32_16x16x32_bf16(b2[nb], a2[mb], acc[nb][mb], 0, 0, 0); }
;     }
.LBB0_593:
	v_lshl_add_u64 v[48:49], v[40:41], 0, s[54:55]
	s_mov_b32 s0, 0x4830000
	v_lshl_add_u64 v[50:51], v[42:43], 0, s[54:55]
	v_add_co_u32_e32 v60, vcc, s0, v48
	s_mov_b32 s0, 0x123c0000
	s_mov_b32 s6, 0x123d2000
	s_mov_b32 s8, 0x123e4000
	s_mov_b32 s10, 0x123f6000
	s_mov_b32 s12, 0x12408000
	s_mov_b32 s14, 0x1241a000
	s_mov_b32 s16, 0x1242c000
	s_mov_b32 s18, 0x1243e000
	v_add_co_u32_e64 v62, s[0:1], s0, v50
	v_add_co_u32_e64 v64, s[6:7], s6, v50
	v_add_co_u32_e64 v66, s[8:9], s8, v50
	v_add_co_u32_e64 v68, s[10:11], s10, v50
	v_add_co_u32_e64 v70, s[12:13], s12, v50
	v_add_co_u32_e64 v72, s[14:15], s14, v50
	v_add_co_u32_e64 v74, s[16:17], s16, v50
	v_add_co_u32_e64 v76, s[18:19], s18, v50
	v_addc_co_u32_e32 v61, vcc, 0, v49, vcc
	v_addc_co_u32_e64 v63, vcc, 0, v51, s[0:1]
	v_addc_co_u32_e64 v65, vcc, 0, v51, s[6:7]
	v_addc_co_u32_e64 v67, vcc, 0, v51, s[8:9]
	v_addc_co_u32_e64 v69, vcc, 0, v51, s[10:11]
	v_addc_co_u32_e64 v71, vcc, 0, v51, s[12:13]
	v_addc_co_u32_e64 v73, vcc, 0, v51, s[14:15]
	v_addc_co_u32_e64 v75, vcc, 0, v51, s[16:17]
	v_addc_co_u32_e64 v77, vcc, 0, v51, s[18:19]
	global_load_dwordx4 v[82:85], v[60:61], off
	global_load_dwordx4 v[86:89], v[62:63], off offset:3072
	global_load_dwordx4 v[90:93], v[64:65], off offset:3072
	s_mov_b32 s0, s38
	s_add_i32 s38, s38, 16
	v_lshl_add_u64 v[40:41], v[40:41], 0, s[40:41]
	s_cmp_lt_i32 s0, -12
	v_lshl_add_u64 v[42:43], v[42:43], 0, s[40:41]
	global_load_dwordx4 v[94:97], v[66:67], off offset:3072
	global_load_dwordx4 v[104:107], v[68:69], off offset:3072
	global_load_dwordx4 v[108:111], v[70:71], off offset:3072
	global_load_dwordx4 v[112:115], v[72:73], off offset:3072
	global_load_dwordx4 v[116:119], v[74:75], off offset:3072
	global_load_dwordx4 v[120:123], v[76:77], off offset:3072
	global_load_dwordx4 v[124:127], v[60:61], off offset:512
	global_load_dwordx4 v[128:131], v[62:63], off offset:3584
	global_load_dwordx4 v[144:147], v[64:65], off offset:3584
	global_load_dwordx4 v[150:153], v[66:67], off offset:3584
	global_load_dwordx4 v[154:157], v[68:69], off offset:3584
	global_load_dwordx4 v[162:165], v[70:71], off offset:3584
	global_load_dwordx4 v[172:175], v[72:73], off offset:3584
	global_load_dwordx4 v[184:187], v[74:75], off offset:3584
	global_load_dwordx4 v[188:191], v[76:77], off offset:3584
	s_waitcnt vmcnt(0)
	v_mfma_f32_16x16x32_bf16 v[28:31], v[82:85], v[86:89], v[28:31]
	v_mfma_f32_16x16x32_bf16 v[24:27], v[82:85], v[90:93], v[24:27]
	v_mfma_f32_16x16x32_bf16 v[16:19], v[82:85], v[94:97], v[16:19]
	v_mfma_f32_16x16x32_bf16 v[12:15], v[82:85], v[104:107], v[12:15]
	v_mfma_f32_16x16x32_bf16 v[8:11], v[82:85], v[108:111], v[8:11]
	v_mfma_f32_16x16x32_bf16 v[4:7], v[82:85], v[112:115], v[4:7]
	v_mfma_f32_16x16x32_bf16 v[0:3], v[82:85], v[116:119], v[0:3]
	v_mfma_f32_16x16x32_bf16 v[20:23], v[82:85], v[120:123], v[20:23]
	v_mfma_f32_16x16x32_bf16 v[28:31], v[124:127], v[128:131], v[28:31]
	v_mfma_f32_16x16x32_bf16 v[24:27], v[124:127], v[144:147], v[24:27]
	v_mfma_f32_16x16x32_bf16 v[16:19], v[124:127], v[150:153], v[16:19]
	v_mfma_f32_16x16x32_bf16 v[12:15], v[124:127], v[154:157], v[12:15]
	v_mfma_f32_16x16x32_bf16 v[8:11], v[124:127], v[162:165], v[8:11]
	v_mfma_f32_16x16x32_bf16 v[4:7], v[124:127], v[172:175], v[4:7]
	v_mfma_f32_16x16x32_bf16 v[0:3], v[124:127], v[184:187], v[0:3]
	v_mfma_f32_16x16x32_bf16 v[20:23], v[124:127], v[188:191], v[20:23]
	s_cbranch_scc1 .LBB0_593

; __device__ __forceinline__ void wave_bias(const bf16_t* A, const bf16_t* Bt, int N, float* BW, int unit, int lane) {
;     const int fr = lane & 15, fq = lane >> 4;
;     f32x4 a0 = (f32x4){0.f, 0.f, 0.f, 0.f}, a1 = a0;
;     const bf16_t* ap = A + (size_t)fr * 1024 + 8 * fq; const bf16_t* bp = Bt + (size_t)(16 * unit + fr) * 1024 + 8 * fq;
; #pragma unroll 8
;     for (int k = 0; k < 1024; k += 32) { const bf16x8 bv = *(const bf16x8*)(bp + k), x0 = *(const bf16x8*)(ap + k), x1 = *(const bf16x8*)(ap + 16 * 1024 + k);
;         a0 = __builtin_amdgcn_mfma_f32_16x16x32_bf16(bv, x0, a0, 0, 0, 0); a1 = __builtin_amdgcn_mfma_f32_16x16x32_bf16(bv, x1, a1, 0, 0, 0); }
;     *(f32x4*)(BW + (size_t)fr * N + 16 * unit + 4 * fq) = a0;
;     if (fr < 8) *(f32x4*)(BW + (size_t)(16 + fr) * N + 16 * unit + 4 * fq) = a1;
; }
; __global__ void __launch_bounds__(512, 2) fwd_kernel(Params P) {
;     ...
;         for (int un = gw; un < 896; un += NGW) {
;             int r = un;
;             if (r < 704) { const int mi = 2 + r / 352, inst = mi == 2 ? 3 : 5; wave_bias(SHB + (size_t)inst * 128 * 1024, WFI + (size_t)mi * 5632 * 1024, 5632, BW + (size_t)mi * 24 * 5632, r % 352, lane); continue; } r -= 704;
;             wave_bias(SHB + (size_t)4 * 128 * 1024, WCI, 3072, BWC, r, lane);
;         }
.LBB0_868:
	v_lshl_add_u64 v[26:27], v[22:23], 0, v[168:169]
	v_add_co_u32_e32 v54, vcc, 0x4b40000, v26
	v_lshl_add_u64 v[38:39], v[24:25], 0, v[168:169]
	s_nop 0
	v_addc_co_u32_e32 v55, vcc, 0, v27, vcc
	global_load_dwordx4 v[68:71], v[54:55], off
	v_add_co_u32_e32 v58, vcc, 0x1e438000, v38
	s_addk_i32 s4, 0x100
	s_nop 0
	v_addc_co_u32_e32 v59, vcc, 0, v39, vcc
	global_load_dwordx4 v[72:75], v[54:55], off offset:64
	global_load_dwordx4 v[76:79], v[58:59], off
	v_add_co_u32_e32 v60, vcc, 0x1e440000, v38
	v_lshl_add_u64 v[24:25], v[24:25], 0, s[6:7]
	s_nop 0
	v_addc_co_u32_e32 v61, vcc, 0, v39, vcc
	global_load_dwordx4 v[82:85], v[58:59], off offset:64
	global_load_dwordx4 v[86:89], v[60:61], off
	s_cmpk_gt_u32 s4, 0x3df
	v_lshl_add_u64 v[22:23], v[22:23], 0, s[6:7]
	global_load_dwordx4 v[90:93], v[60:61], off offset:64
	global_load_dwordx4 v[94:97], v[54:55], off offset:128
	global_load_dwordx4 v[104:107], v[54:55], off offset:192
	global_load_dwordx4 v[108:111], v[54:55], off offset:256
	global_load_dwordx4 v[112:115], v[58:59], off offset:128
	global_load_dwordx4 v[116:119], v[58:59], off offset:192
	global_load_dwordx4 v[120:123], v[60:61], off offset:128
	global_load_dwordx4 v[124:127], v[60:61], off offset:192
	global_load_dwordx4 v[128:131], v[54:55], off offset:320
	global_load_dwordx4 v[142:145], v[54:55], off offset:384
	global_load_dwordx4 v[146:149], v[54:55], off offset:448
	global_load_dwordx4 v[150:153], v[58:59], off offset:256
	s_nop 0
	global_load_dwordx4 v[154:157], v[58:59], off offset:320
	global_load_dwordx4 v[158:161], v[60:61], off offset:256
	global_load_dwordx4 v[162:165], v[60:61], off offset:320
	global_load_dwordx4 v[170:173], v[58:59], off offset:384
	global_load_dwordx4 v[194:197], v[60:61], off offset:384
	global_load_dwordx4 v[198:201], v[58:59], off offset:448
	global_load_dwordx4 v[202:205], v[60:61], off offset:448
	s_waitcnt vmcnt(0)
	v_mfma_f32_16x16x32_bf16 v[0:3], v[68:71], v[76:79], v[0:3]
	v_mfma_f32_16x16x32_bf16 v[4:7], v[68:71], v[86:89], v[4:7]
	v_mfma_f32_16x16x32_bf16 v[0:3], v[72:75], v[82:85], v[0:3]
	v_mfma_f32_16x16x32_bf16 v[4:7], v[72:75], v[90:93], v[4:7]
	v_mfma_f32_16x16x32_bf16 v[0:3], v[94:97], v[112:115], v[0:3]
	v_mfma_f32_16x16x32_bf16 v[0:3], v[104:107], v[116:119], v[0:3]
	v_mfma_f32_16x16x32_bf16 v[4:7], v[94:97], v[120:123], v[4:7]
	v_mfma_f32_16x16x32_bf16 v[4:7], v[104:107], v[124:127], v[4:7]
	v_mfma_f32_16x16x32_bf16 v[0:3], v[108:111], v[150:153], v[0:3]
	v_mfma_f32_16x16x32_bf16 v[4:7], v[108:111], v[158:161], v[4:7]
	v_mfma_f32_16x16x32_bf16 v[0:3], v[128:131], v[154:157], v[0:3]
	v_mfma_f32_16x16x32_bf16 v[4:7], v[128:131], v[162:165], v[4:7]
	v_mfma_f32_16x16x32_bf16 v[0:3], v[142:145], v[170:173], v[0:3]
	v_mfma_f32_16x16x32_bf16 v[4:7], v[142:145], v[194:197], v[4:7]
	v_mfma_f32_16x16x32_bf16 v[0:3], v[146:149], v[198:201], v[0:3]
	v_mfma_f32_16x16x32_bf16 v[4:7], v[146:149], v[202:205], v[4:7]
	s_cbranch_scc0 .LBB0_868
	s_lshl_b32 s4, s15, 4
	s_addk_i32 s4, 0xd400
	v_lshl_add_u64 v[22:23], s[4:5], 2, v[12:13]
	s_nop 1
	global_store_dwordx4 v[22:23], v[0:3], off
	s_and_saveexec_b64 s[8:9], s[0:1]
	s_cbranch_execz .LBB0_871
	v_lshl_add_u64 v[0:1], s[4:5], 2, v[14:15]
	global_store_dwordx4 v[0:1], v[4:7], off

; __device__ __forceinline__ void wave_bias(const bf16_t* A, const bf16_t* Bt, int N, float* BW, int unit, int lane) {
;     const int fr = lane & 15, fq = lane >> 4;
;     f32x4 a0 = (f32x4){0.f, 0.f, 0.f, 0.f}, a1 = a0;
;     const bf16_t* ap = A + (size_t)fr * 1024 + 8 * fq; const bf16_t* bp = Bt + (size_t)(16 * unit + fr) * 1024 + 8 * fq;
; #pragma unroll 8
;     for (int k = 0; k < 1024; k += 32) { const bf16x8 bv = *(const bf16x8*)(bp + k), x0 = *(const bf16x8*)(ap + k), x1 = *(const bf16x8*)(ap + 16 * 1024 + k);
;         a0 = __builtin_amdgcn_mfma_f32_16x16x32_bf16(bv, x0, a0, 0, 0, 0); a1 = __builtin_amdgcn_mfma_f32_16x16x32_bf16(bv, x1, a1, 0, 0, 0); }
;     *(f32x4*)(BW + (size_t)fr * N + 16 * unit + 4 * fq) = a0;
;     if (fr < 8) *(f32x4*)(BW + (size_t)(16 + fr) * N + 16 * unit + 4 * fq) = a1;
; }
; __global__ void __launch_bounds__(512, 2) fwd_kernel(Params P) {
;     ...
;         for (int un = gw; un < 896; un += NGW) {
;             int r = un;
;             if (r < 704) { const int mi = 2 + r / 352, inst = mi == 2 ? 3 : 5; wave_bias(SHB + (size_t)inst * 128 * 1024, WFI + (size_t)mi * 5632 * 1024, 5632, BW + (size_t)mi * 24 * 5632, r % 352, lane); continue; } r -= 704;
;             wave_bias(SHB + (size_t)4 * 128 * 1024, WCI, 3072, BWC, r, lane);
;         }
.LBB0_873:
	v_lshl_add_u64 v[38:39], v[22:23], 0, v[168:169]
	v_add_co_u32_e32 v58, vcc, s13, v38
	v_lshl_add_u64 v[54:55], v[24:25], 0, v[168:169]
	s_nop 0
	v_addc_co_u32_e32 v59, vcc, 0, v39, vcc
	global_load_dwordx4 v[68:71], v[54:55], off offset:-256
	global_load_dwordx4 v[72:75], v[54:55], off offset:-192
	global_load_dwordx4 v[76:79], v[58:59], off
	v_add_co_u32_e32 v60, vcc, s14, v38
	s_addk_i32 s4, 0x100
	s_nop 0
	v_addc_co_u32_e32 v61, vcc, 0, v39, vcc
	global_load_dwordx4 v[82:85], v[58:59], off offset:64
	global_load_dwordx4 v[86:89], v[60:61], off
	v_lshl_add_u64 v[22:23], v[22:23], 0, s[6:7]
	s_cmpk_gt_u32 s4, 0x3df
	v_lshl_add_u64 v[24:25], v[24:25], 0, s[6:7]
	global_load_dwordx4 v[90:93], v[60:61], off offset:64
	global_load_dwordx4 v[94:97], v[54:55], off offset:-128
	global_load_dwordx4 v[104:107], v[54:55], off offset:-64
	global_load_dwordx4 v[108:111], v[54:55], off
	global_load_dwordx4 v[112:115], v[58:59], off offset:128
	global_load_dwordx4 v[116:119], v[58:59], off offset:192
	global_load_dwordx4 v[120:123], v[60:61], off offset:128
	global_load_dwordx4 v[124:127], v[60:61], off offset:192
	global_load_dwordx4 v[128:131], v[54:55], off offset:64
	global_load_dwordx4 v[142:145], v[54:55], off offset:128
	global_load_dwordx4 v[146:149], v[54:55], off offset:192
	global_load_dwordx4 v[150:153], v[58:59], off offset:256
	s_nop 0
	global_load_dwordx4 v[154:157], v[58:59], off offset:320
	global_load_dwordx4 v[158:161], v[60:61], off offset:256
	global_load_dwordx4 v[162:165], v[60:61], off offset:320
	global_load_dwordx4 v[170:173], v[58:59], off offset:384
	global_load_dwordx4 v[194:197], v[60:61], off offset:384
	global_load_dwordx4 v[198:201], v[58:59], off offset:448
	global_load_dwordx4 v[202:205], v[60:61], off offset:448
	s_waitcnt vmcnt(0)
	v_mfma_f32_16x16x32_bf16 v[0:3], v[68:71], v[76:79], v[0:3]
	v_mfma_f32_16x16x32_bf16 v[4:7], v[68:71], v[86:89], v[4:7]
	v_mfma_f32_16x16x32_bf16 v[0:3], v[72:75], v[82:85], v[0:3]
	v_mfma_f32_16x16x32_bf16 v[4:7], v[72:75], v[90:93], v[4:7]
	v_mfma_f32_16x16x32_bf16 v[0:3], v[94:97], v[112:115], v[0:3]
	v_mfma_f32_16x16x32_bf16 v[0:3], v[104:107], v[116:119], v[0:3]
	v_mfma_f32_16x16x32_bf16 v[4:7], v[94:97], v[120:123], v[4:7]
	v_mfma_f32_16x16x32_bf16 v[4:7], v[104:107], v[124:127], v[4:7]
	v_mfma_f32_16x16x32_bf16 v[0:3], v[108:111], v[150:153], v[0:3]
	v_mfma_f32_16x16x32_bf16 v[4:7], v[108:111], v[158:161], v[4:7]
	v_mfma_f32_16x16x32_bf16 v[0:3], v[128:131], v[154:157], v[0:3]
	v_mfma_f32_16x16x32_bf16 v[4:7], v[128:131], v[162:165], v[4:7]
	v_mfma_f32_16x16x32_bf16 v[0:3], v[142:145], v[170:173], v[0:3]
	v_mfma_f32_16x16x32_bf16 v[4:7], v[142:145], v[194:197], v[4:7]
	v_mfma_f32_16x16x32_bf16 v[0:3], v[146:149], v[198:201], v[0:3]
	v_mfma_f32_16x16x32_bf16 v[4:7], v[146:149], v[202:205], v[4:7]
	s_cbranch_scc0 .LBB0_873
	s_add_i32 s9, s9, 2
	v_mad_i64_i32 v[22:23], s[16:17], s9, v11, v[16:17]
	s_ashr_i32 s9, s8, 31
	v_lshl_add_u64 v[22:23], s[8:9], 2, v[22:23]
	v_lshlrev_b32_e32 v8, 2, v10
	v_lshl_add_u64 v[22:23], v[22:23], 0, v[8:9]
	global_store_dwordx4 v[22:23], v[0:3], off
	s_and_saveexec_b64 s[8:9], s[0:1]
	s_cbranch_execz .LBB0_863
	v_add_co_u32_e32 v0, vcc, 0x58000, v22
	s_nop 1
	v_addc_co_u32_e32 v1, vcc, 0, v23, vcc
	global_store_dwordx4 v[0:1], v[4:7], off
	s_branch .LBB0_863

; template <int NB>
; __device__ __forceinline__ void small_core(LAS unsigned char* lds, const bf16_t* A, int lda, const bf16_t* B0, const bf16_t* B1, int K, f32x4 (&out)[NB]) {
;     ...
;     for (; st + 8 < nsteps; st += 16) {
;         const int k = st * 32, k2 = k + 256;
;         bf16x8 b[NB], b2[NB]; b[0] = *(const bf16x8*)(bp0 + k); b2[0] = *(const bf16x8*)(bp0 + k2);
;         if (NB == 2) { b[NB - 1] = *(const bf16x8*)(bp1 + k); b2[NB - 1] = *(const bf16x8*)(bp1 + k2); }
;         bf16x8 a[8], a2[8];
; #pragma unroll
;         for (int mb = 0; mb < 8; ++mb) { a[mb] = *(const bf16x8*)(ap + (size_t)(16 * mb) * lda + k); a2[mb] = *(const bf16x8*)(ap + (size_t)(16 * mb) * lda + k2); }
; #pragma unroll
;         for (int mb = 0; mb < 8; ++mb)
; #pragma unroll
;             for (int nb = 0; nb < NB; ++nb) { acc[nb][mb] = __builtin_amdgcn_mfma_f32_16x16x32_bf16(b[nb], a[mb], acc[nb][mb], 0, 0, 0);
;                 acc[nb][mb] = __builtin_amdgcn_mfma_f32_16x16x32_bf16(b2[nb], a2[mb], acc[nb][mb], 0, 0, 0); }
;     }
;     if (st < nsteps) {
;         const int k = st * 32;
;         bf16x8 b[NB]; b[0] = *(const bf16x8*)(bp0 + k); if (NB == 2) b[NB - 1] = *(const bf16x8*)(bp1 + k);
;         bf16x8 a[8];
; #pragma unroll
;         for (int mb = 0; mb < 8; ++mb) a[mb] = *(const bf16x8*)(ap + (size_t)(16 * mb) * lda + k);
; #pragma unroll
;         for (int mb = 0; mb < 8; ++mb)
; #pragma unroll
;             for (int nb = 0; nb < NB; ++nb) acc[nb][mb] = __builtin_amdgcn_mfma_f32_16x16x32_bf16(b[nb], a[mb], acc[nb][mb], 0, 0, 0);
;     }
.LBB0_881:
	s_ashr_i32 s53, s52, 31
	s_lshl_b64 s[46:47], s[52:53], 1
	v_lshl_add_u64 v[100:101], v[48:49], 0, s[46:47]
	v_lshl_add_u64 v[108:109], v[46:47], 0, s[46:47]
	v_lshl_add_u64 v[112:113], v[50:51], 0, s[46:47]
	v_lshl_add_u64 v[114:115], v[52:53], 0, s[46:47]
	v_lshl_add_u64 v[116:117], v[54:55], 0, s[46:47]
	v_lshl_add_u64 v[118:119], v[56:57], 0, s[46:47]
	v_lshl_add_u64 v[120:121], v[58:59], 0, s[46:47]
	v_lshl_add_u64 v[122:123], v[60:61], 0, s[46:47]
	v_lshl_add_u64 v[124:125], v[62:63], 0, s[46:47]
	global_load_dwordx4 v[126:129], v[100:101], off
	global_load_dwordx4 v[130:133], v[108:109], off
	global_load_dwordx4 v[142:145], v[112:113], off
	global_load_dwordx4 v[146:149], v[114:115], off
	global_load_dwordx4 v[150:153], v[116:117], off
	global_load_dwordx4 v[154:157], v[118:119], off
	global_load_dwordx4 v[158:161], v[120:121], off
	global_load_dwordx4 v[162:165], v[122:123], off
	s_nop 0
	global_load_dwordx4 v[166:169], v[100:101], off offset:512
	s_nop 0
	global_load_dwordx4 v[170:173], v[124:125], off
	s_nop 0
	global_load_dwordx4 v[194:197], v[108:109], off offset:512
	s_mov_b32 s33, s8
	s_add_i32 s8, s8, 16
	s_addk_i32 s52, 0x200
	s_cmp_lt_i32 s33, 8
	global_load_dwordx4 v[198:201], v[112:113], off offset:512
	global_load_dwordx4 v[202:205], v[114:115], off offset:512
	global_load_dwordx4 v[206:209], v[116:117], off offset:512
	global_load_dwordx4 v[210:213], v[118:119], off offset:512
	global_load_dwordx4 v[214:217], v[120:121], off offset:512
	global_load_dwordx4 v[218:221], v[122:123], off offset:512
	global_load_dwordx4 v[222:225], v[124:125], off offset:512
	s_waitcnt vmcnt(0)
	v_mfma_f32_16x16x32_bf16 v[28:31], v[126:129], v[130:133], v[28:31]
	v_mfma_f32_16x16x32_bf16 v[24:27], v[126:129], v[142:145], v[24:27]
	v_mfma_f32_16x16x32_bf16 v[20:23], v[126:129], v[146:149], v[20:23]
	v_mfma_f32_16x16x32_bf16 v[16:19], v[126:129], v[150:153], v[16:19]
	v_mfma_f32_16x16x32_bf16 v[12:15], v[126:129], v[154:157], v[12:15]
	v_mfma_f32_16x16x32_bf16 v[8:11], v[126:129], v[158:161], v[8:11]
	v_mfma_f32_16x16x32_bf16 v[4:7], v[126:129], v[162:165], v[4:7]
	v_mfma_f32_16x16x32_bf16 v[0:3], v[126:129], v[170:173], v[0:3]
	v_mfma_f32_16x16x32_bf16 v[28:31], v[166:169], v[194:197], v[28:31]
	v_mfma_f32_16x16x32_bf16 v[24:27], v[166:169], v[198:201], v[24:27]
	v_mfma_f32_16x16x32_bf16 v[20:23], v[166:169], v[202:205], v[20:23]
	v_mfma_f32_16x16x32_bf16 v[16:19], v[166:169], v[206:209], v[16:19]
	v_mfma_f32_16x16x32_bf16 v[12:15], v[166:169], v[210:213], v[12:15]
	v_mfma_f32_16x16x32_bf16 v[8:11], v[166:169], v[214:217], v[8:11]
	v_mfma_f32_16x16x32_bf16 v[4:7], v[166:169], v[218:221], v[4:7]
	v_mfma_f32_16x16x32_bf16 v[0:3], v[166:169], v[222:225], v[0:3]
	s_cbranch_scc1 .LBB0_881
.LBB0_882:
	s_cmp_gt_u32 s8, 31
	s_cbranch_scc1 .LBB0_884
	s_lshl_b32 s8, s8, 6
	v_lshl_add_u64 v[48:49], v[48:49], 0, s[8:9]
	global_load_dwordx4 v[126:129], v[48:49], off
	v_lshl_add_u64 v[46:47], v[46:47], 0, s[8:9]
	global_load_dwordx4 v[130:133], v[46:47], off
	v_add_co_u32_e32 v56, vcc, 0x8000, v46
	v_addc_co_u32_e32 v57, vcc, 0, v47, vcc
	v_add_co_u32_e32 v60, vcc, 0x10000, v46
	global_load_dwordx4 v[142:145], v[56:57], off
	s_nop 0
	v_addc_co_u32_e32 v61, vcc, 0, v47, vcc
	v_add_co_u32_e32 v68, vcc, 0x18000, v46
	v_addc_co_u32_e32 v69, vcc, 0, v47, vcc
	v_add_co_u32_e32 v72, vcc, 0x20000, v46
	global_load_dwordx4 v[146:149], v[60:61], off
	s_nop 0
	global_load_dwordx4 v[150:153], v[68:69], off
	v_addc_co_u32_e32 v73, vcc, 0, v47, vcc
	v_add_co_u32_e32 v76, vcc, 0x28000, v46
	global_load_dwordx4 v[154:157], v[72:73], off
	s_nop 0
	v_addc_co_u32_e32 v77, vcc, 0, v47, vcc
	global_load_dwordx4 v[158:161], v[76:77], off
	v_add_co_u32_e32 v56, vcc, 0x30000, v46
	v_addc_co_u32_e32 v57, vcc, 0, v47, vcc
	v_add_co_u32_e32 v46, vcc, 0x38000, v46
	global_load_dwordx4 v[162:165], v[56:57], off
	s_nop 0
	v_addc_co_u32_e32 v47, vcc, 0, v47, vcc
	global_load_dwordx4 v[166:169], v[46:47], off
	s_waitcnt vmcnt(0)
	v_mfma_f32_16x16x32_bf16 v[28:31], v[126:129], v[130:133], v[28:31]
	v_mfma_f32_16x16x32_bf16 v[24:27], v[126:129], v[142:145], v[24:27]
	v_mfma_f32_16x16x32_bf16 v[8:11], v[126:129], v[158:161], v[8:11]
	v_mfma_f32_16x16x32_bf16 v[20:23], v[126:129], v[146:149], v[20:23]
	v_mfma_f32_16x16x32_bf16 v[16:19], v[126:129], v[150:153], v[16:19]
	v_mfma_f32_16x16x32_bf16 v[12:15], v[126:129], v[154:157], v[12:15]
	v_mfma_f32_16x16x32_bf16 v[4:7], v[126:129], v[162:165], v[4:7]
	v_mfma_f32_16x16x32_bf16 v[0:3], v[126:129], v[166:169], v[0:3]

; template <int NB>
; __device__ __forceinline__ void small_core(LAS unsigned char* lds, const bf16_t* A, int lda, const bf16_t* B0, const bf16_t* B1, int K, f32x4 (&out)[NB]) {
;     ...
;     for (; st + 8 < nsteps; st += 16) {
;         const int k = st * 32, k2 = k + 256;
;         bf16x8 b[NB], b2[NB]; b[0] = *(const bf16x8*)(bp0 + k); b2[0] = *(const bf16x8*)(bp0 + k2);
;         if (NB == 2) { b[NB - 1] = *(const bf16x8*)(bp1 + k); b2[NB - 1] = *(const bf16x8*)(bp1 + k2); }
;         bf16x8 a[8], a2[8];
; #pragma unroll
;         for (int mb = 0; mb < 8; ++mb) { a[mb] = *(const bf16x8*)(ap + (size_t)(16 * mb) * lda + k); a2[mb] = *(const bf16x8*)(ap + (size_t)(16 * mb) * lda + k2); }
; #pragma unroll
;         for (int mb = 0; mb < 8; ++mb)
; #pragma unroll
;             for (int nb = 0; nb < NB; ++nb) { acc[nb][mb] = __builtin_amdgcn_mfma_f32_16x16x32_bf16(b[nb], a[mb], acc[nb][mb], 0, 0, 0);
;                 acc[nb][mb] = __builtin_amdgcn_mfma_f32_16x16x32_bf16(b2[nb], a2[mb], acc[nb][mb], 0, 0, 0); }
;     }
.LBB0_985:
	s_ashr_i32 s41, s40, 31
	s_lshl_b64 s[46:47], s[40:41], 1
	v_lshl_add_u64 v[106:107], v[78:79], 0, s[46:47]
	v_lshl_add_u64 v[118:119], v[80:81], 0, s[46:47]
	v_lshl_add_u64 v[110:111], v[76:77], 0, s[46:47]
	global_load_dwordx4 v[152:155], v[106:107], off
	global_load_dwordx4 v[156:159], v[110:111], off
	s_nop 0
	global_load_dwordx4 v[160:163], v[106:107], off offset:512
	s_nop 0
	global_load_dwordx4 v[164:167], v[110:111], off offset:512
	s_nop 0
	global_load_dwordx4 v[168:171], v[118:119], off
	s_nop 0
	global_load_dwordx4 v[172:175], v[118:119], off offset:512
	v_lshl_add_u64 v[122:123], v[2:3], 0, s[46:47]
	v_lshl_add_u64 v[126:127], v[82:83], 0, s[46:47]
	v_lshl_add_u64 v[130:131], v[84:85], 0, s[46:47]
	v_lshl_add_u64 v[134:135], v[86:87], 0, s[46:47]
	v_lshl_add_u64 v[138:139], v[88:89], 0, s[46:47]
	v_lshl_add_u64 v[142:143], v[90:91], 0, s[46:47]
	v_lshl_add_u64 v[150:151], v[92:93], 0, s[46:47]
	s_mov_b32 s41, s0
	s_add_i32 s0, s0, 16
	s_addk_i32 s40, 0x200
	s_cmp_lt_i32 s41, 8
	global_load_dwordx4 v[194:197], v[122:123], off
	s_nop 0
	global_load_dwordx4 v[198:201], v[122:123], off offset:512
	global_load_dwordx4 v[202:205], v[126:127], off
	s_nop 0
	global_load_dwordx4 v[206:209], v[126:127], off offset:512
	global_load_dwordx4 v[210:213], v[130:131], off
	s_nop 0
	global_load_dwordx4 v[214:217], v[130:131], off offset:512
	global_load_dwordx4 v[218:221], v[134:135], off
	s_nop 0
	global_load_dwordx4 v[222:225], v[134:135], off offset:512
	global_load_dwordx4 v[232:235], v[138:139], off
	s_nop 0
	global_load_dwordx4 v[240:243], v[138:139], off offset:512
	global_load_dwordx4 v[248:251], v[142:143], off
	s_nop 0
	global_load_dwordx4 v[98:101], v[142:143], off offset:512
	s_nop 0
	global_load_dwordx4 v[102:105], v[150:151], off
	global_load_dwordx4 v[114:117], v[150:151], off offset:512
	s_waitcnt vmcnt(0)
	v_mfma_f32_16x16x32_bf16 v[40:43], v[152:155], v[156:159], v[40:43]
	v_mfma_f32_16x16x32_bf16 v[64:67], v[168:171], v[156:159], v[64:67]
	v_mfma_f32_16x16x32_bf16 v[40:43], v[160:163], v[164:167], v[40:43]
	v_mfma_f32_16x16x32_bf16 v[64:67], v[172:175], v[164:167], v[64:67]
	v_mfma_f32_16x16x32_bf16 v[36:39], v[152:155], v[194:197], v[36:39]
	v_mfma_f32_16x16x32_bf16 v[60:63], v[168:171], v[194:197], v[60:63]
	v_mfma_f32_16x16x32_bf16 v[36:39], v[160:163], v[198:201], v[36:39]
	v_mfma_f32_16x16x32_bf16 v[60:63], v[172:175], v[198:201], v[60:63]
	v_mfma_f32_16x16x32_bf16 v[24:27], v[152:155], v[202:205], v[24:27]
	v_mfma_f32_16x16x32_bf16 v[56:59], v[168:171], v[202:205], v[56:59]
	v_mfma_f32_16x16x32_bf16 v[24:27], v[160:163], v[206:209], v[24:27]
	v_mfma_f32_16x16x32_bf16 v[56:59], v[172:175], v[206:209], v[56:59]
	v_mfma_f32_16x16x32_bf16 v[20:23], v[152:155], v[210:213], v[20:23]
	v_mfma_f32_16x16x32_bf16 v[52:55], v[168:171], v[210:213], v[52:55]
	v_mfma_f32_16x16x32_bf16 v[20:23], v[160:163], v[214:217], v[20:23]
	v_mfma_f32_16x16x32_bf16 v[52:55], v[172:175], v[214:217], v[52:55]
	v_mfma_f32_16x16x32_bf16 v[16:19], v[152:155], v[218:221], v[16:19]
	v_mfma_f32_16x16x32_bf16 v[48:51], v[168:171], v[218:221], v[48:51]
	v_mfma_f32_16x16x32_bf16 v[16:19], v[160:163], v[222:225], v[16:19]
	v_mfma_f32_16x16x32_bf16 v[48:51], v[172:175], v[222:225], v[48:51]
	v_mfma_f32_16x16x32_bf16 v[12:15], v[152:155], v[232:235], v[12:15]
	v_mfma_f32_16x16x32_bf16 v[44:47], v[168:171], v[232:235], v[44:47]
	v_mfma_f32_16x16x32_bf16 v[12:15], v[160:163], v[240:243], v[12:15]
	v_mfma_f32_16x16x32_bf16 v[44:47], v[172:175], v[240:243], v[44:47]
	v_mfma_f32_16x16x32_bf16 v[8:11], v[152:155], v[248:251], v[8:11]
	v_mfma_f32_16x16x32_bf16 v[28:31], v[168:171], v[248:251], v[28:31]
	v_mfma_f32_16x16x32_bf16 v[4:7], v[152:155], v[102:105], v[4:7]
	v_mfma_f32_16x16x32_bf16 v[32:35], v[168:171], v[102:105], v[32:35]
	v_mfma_f32_16x16x32_bf16 v[8:11], v[160:163], v[98:101], v[8:11]
	v_mfma_f32_16x16x32_bf16 v[28:31], v[172:175], v[98:101], v[28:31]
	v_mfma_f32_16x16x32_bf16 v[4:7], v[160:163], v[114:117], v[4:7]
	v_mfma_f32_16x16x32_bf16 v[32:35], v[172:175], v[114:117], v[32:35]
	s_cbranch_scc1 .LBB0_985

; template <int NB>
; __device__ __forceinline__ void small_core(LAS unsigned char* lds, const bf16_t* A, int lda, const bf16_t* B0, const bf16_t* B1, int K, f32x4 (&out)[NB]) {
;     ...
;     for (; st + 8 < nsteps; st += 16) {
;         const int k = st * 32, k2 = k + 256;
;         bf16x8 b[NB], b2[NB]; b[0] = *(const bf16x8*)(bp0 + k); b2[0] = *(const bf16x8*)(bp0 + k2);
;         if (NB == 2) { b[NB - 1] = *(const bf16x8*)(bp1 + k); b2[NB - 1] = *(const bf16x8*)(bp1 + k2); }
;         bf16x8 a[8], a2[8];
; #pragma unroll
;         for (int mb = 0; mb < 8; ++mb) { a[mb] = *(const bf16x8*)(ap + (size_t)(16 * mb) * lda + k); a2[mb] = *(const bf16x8*)(ap + (size_t)(16 * mb) * lda + k2); }
; #pragma unroll
;         for (int mb = 0; mb < 8; ++mb)
; #pragma unroll
;             for (int nb = 0; nb < NB; ++nb) { acc[nb][mb] = __builtin_amdgcn_mfma_f32_16x16x32_bf16(b[nb], a[mb], acc[nb][mb], 0, 0, 0);
;                 acc[nb][mb] = __builtin_amdgcn_mfma_f32_16x16x32_bf16(b2[nb], a2[mb], acc[nb][mb], 0, 0, 0); }
;     }
;     if (st < nsteps) {
;         const int k = st * 32;
;         bf16x8 b[NB]; b[0] = *(const bf16x8*)(bp0 + k); if (NB == 2) b[NB - 1] = *(const bf16x8*)(bp1 + k);
;         bf16x8 a[8];
; #pragma unroll
;         for (int mb = 0; mb < 8; ++mb) a[mb] = *(const bf16x8*)(ap + (size_t)(16 * mb) * lda + k);
; #pragma unroll
;         for (int mb = 0; mb < 8; ++mb)
; #pragma unroll
;             for (int nb = 0; nb < NB; ++nb) acc[nb][mb] = __builtin_amdgcn_mfma_f32_16x16x32_bf16(b[nb], a[mb], acc[nb][mb], 0, 0, 0);
;     }
.LBB0_1061:
	s_ashr_i32 s53, s52, 31
	s_lshl_b64 s[56:57], s[52:53], 1
	v_lshl_add_u64 v[100:101], v[48:49], 0, s[56:57]
	v_lshl_add_u64 v[108:109], v[46:47], 0, s[56:57]
	v_lshl_add_u64 v[112:113], v[50:51], 0, s[56:57]
	v_lshl_add_u64 v[114:115], v[52:53], 0, s[56:57]
	v_lshl_add_u64 v[116:117], v[54:55], 0, s[56:57]
	v_lshl_add_u64 v[118:119], v[56:57], 0, s[56:57]
	v_lshl_add_u64 v[120:121], v[58:59], 0, s[56:57]
	v_lshl_add_u64 v[122:123], v[60:61], 0, s[56:57]
	v_lshl_add_u64 v[124:125], v[62:63], 0, s[56:57]
	global_load_dwordx4 v[126:129], v[100:101], off
	global_load_dwordx4 v[130:133], v[108:109], off
	global_load_dwordx4 v[142:145], v[112:113], off
	global_load_dwordx4 v[146:149], v[114:115], off
	global_load_dwordx4 v[150:153], v[116:117], off
	global_load_dwordx4 v[154:157], v[118:119], off
	global_load_dwordx4 v[158:161], v[120:121], off
	global_load_dwordx4 v[162:165], v[122:123], off
	s_nop 0
	global_load_dwordx4 v[166:169], v[100:101], off offset:512
	s_nop 0
	global_load_dwordx4 v[170:173], v[124:125], off
	s_nop 0
	global_load_dwordx4 v[194:197], v[108:109], off offset:512
	s_mov_b32 s53, s4
	s_add_i32 s4, s4, 16
	s_addk_i32 s52, 0x200
	s_cmp_lt_i32 s53, 64
	global_load_dwordx4 v[198:201], v[112:113], off offset:512
	global_load_dwordx4 v[202:205], v[114:115], off offset:512
	global_load_dwordx4 v[206:209], v[116:117], off offset:512
	global_load_dwordx4 v[210:213], v[118:119], off offset:512
	global_load_dwordx4 v[214:217], v[120:121], off offset:512
	global_load_dwordx4 v[218:221], v[122:123], off offset:512
	global_load_dwordx4 v[222:225], v[124:125], off offset:512
	s_waitcnt vmcnt(0)
	v_mfma_f32_16x16x32_bf16 v[28:31], v[126:129], v[130:133], v[28:31]
	v_mfma_f32_16x16x32_bf16 v[24:27], v[126:129], v[142:145], v[24:27]
	v_mfma_f32_16x16x32_bf16 v[20:23], v[126:129], v[146:149], v[20:23]
	v_mfma_f32_16x16x32_bf16 v[16:19], v[126:129], v[150:153], v[16:19]
	v_mfma_f32_16x16x32_bf16 v[12:15], v[126:129], v[154:157], v[12:15]
	v_mfma_f32_16x16x32_bf16 v[8:11], v[126:129], v[158:161], v[8:11]
	v_mfma_f32_16x16x32_bf16 v[4:7], v[126:129], v[162:165], v[4:7]
	v_mfma_f32_16x16x32_bf16 v[0:3], v[126:129], v[170:173], v[0:3]
	v_mfma_f32_16x16x32_bf16 v[28:31], v[166:169], v[194:197], v[28:31]
	v_mfma_f32_16x16x32_bf16 v[24:27], v[166:169], v[198:201], v[24:27]
	v_mfma_f32_16x16x32_bf16 v[20:23], v[166:169], v[202:205], v[20:23]
	v_mfma_f32_16x16x32_bf16 v[16:19], v[166:169], v[206:209], v[16:19]
	v_mfma_f32_16x16x32_bf16 v[12:15], v[166:169], v[210:213], v[12:15]
	v_mfma_f32_16x16x32_bf16 v[8:11], v[166:169], v[214:217], v[8:11]
	v_mfma_f32_16x16x32_bf16 v[4:7], v[166:169], v[218:221], v[4:7]
	v_mfma_f32_16x16x32_bf16 v[0:3], v[166:169], v[222:225], v[0:3]
	s_cbranch_scc1 .LBB0_1061
.LBB0_1062:
	s_cmpk_gt_u32 s4, 0x57
	s_cbranch_scc1 .LBB0_1064
	s_lshl_b32 s4, s4, 6
	v_lshl_add_u64 v[48:49], v[48:49], 0, s[4:5]
	global_load_dwordx4 v[126:129], v[48:49], off
	v_lshl_add_u64 v[46:47], v[46:47], 0, s[4:5]
	global_load_dwordx4 v[130:133], v[46:47], off
	v_add_co_u32_e32 v56, vcc, 0x16000, v46
	v_addc_co_u32_e32 v57, vcc, 0, v47, vcc
	v_add_co_u32_e32 v60, vcc, 0x2c000, v46
	s_nop 1
	v_addc_co_u32_e32 v61, vcc, 0, v47, vcc
	v_add_co_u32_e32 v68, vcc, 0x42000, v46
	global_load_dwordx4 v[142:145], v[56:57], off
	s_nop 0
	global_load_dwordx4 v[146:149], v[60:61], off
	v_addc_co_u32_e32 v69, vcc, 0, v47, vcc
	v_add_co_u32_e32 v72, vcc, 0x58000, v46
	v_addc_co_u32_e32 v73, vcc, 0, v47, vcc
	global_load_dwordx4 v[150:153], v[72:73], off
	v_add_co_u32_e32 v72, vcc, 0x6e000, v46
	s_nop 0
	v_addc_co_u32_e32 v73, vcc, 0, v47, vcc
	v_add_co_u32_e32 v60, vcc, 0x84000, v46
	global_load_dwordx4 v[154:157], v[72:73], off
	s_nop 0
	v_addc_co_u32_e32 v61, vcc, 0, v47, vcc
	global_load_dwordx4 v[158:161], v[60:61], off
	v_add_co_u32_e32 v46, vcc, 0x9a000, v46
	global_load_dwordx4 v[162:165], v[68:69], off
	s_nop 0
	v_addc_co_u32_e32 v47, vcc, 0, v47, vcc
	global_load_dwordx4 v[166:169], v[46:47], off
	s_waitcnt vmcnt(0)
	v_mfma_f32_16x16x32_bf16 v[28:31], v[126:129], v[130:133], v[28:31]
	v_mfma_f32_16x16x32_bf16 v[20:23], v[126:129], v[146:149], v[20:23]
	v_mfma_f32_16x16x32_bf16 v[24:27], v[126:129], v[142:145], v[24:27]
	v_mfma_f32_16x16x32_bf16 v[12:15], v[126:129], v[150:153], v[12:15]
	v_mfma_f32_16x16x32_bf16 v[4:7], v[126:129], v[158:161], v[4:7]
	v_mfma_f32_16x16x32_bf16 v[16:19], v[126:129], v[162:165], v[16:19]
	v_mfma_f32_16x16x32_bf16 v[8:11], v[126:129], v[154:157], v[8:11]
	v_mfma_f32_16x16x32_bf16 v[0:3], v[126:129], v[166:169], v[0:3]

; template <int NB>
; __device__ __forceinline__ void small_core(LAS unsigned char* lds, const bf16_t* A, int lda, const bf16_t* B0, const bf16_t* B1, int K, f32x4 (&out)[NB]) {
;     ...
;     for (; st + 8 < nsteps; st += 16) {
;         const int k = st * 32, k2 = k + 256;
;         bf16x8 b[NB], b2[NB]; b[0] = *(const bf16x8*)(bp0 + k); b2[0] = *(const bf16x8*)(bp0 + k2);
;         if (NB == 2) { b[NB - 1] = *(const bf16x8*)(bp1 + k); b2[NB - 1] = *(const bf16x8*)(bp1 + k2); }
;         bf16x8 a[8], a2[8];
; #pragma unroll
;         for (int mb = 0; mb < 8; ++mb) { a[mb] = *(const bf16x8*)(ap + (size_t)(16 * mb) * lda + k); a2[mb] = *(const bf16x8*)(ap + (size_t)(16 * mb) * lda + k2); }
; #pragma unroll
;         for (int mb = 0; mb < 8; ++mb)
; #pragma unroll
;             for (int nb = 0; nb < NB; ++nb) { acc[nb][mb] = __builtin_amdgcn_mfma_f32_16x16x32_bf16(b[nb], a[mb], acc[nb][mb], 0, 0, 0);
;                 acc[nb][mb] = __builtin_amdgcn_mfma_f32_16x16x32_bf16(b2[nb], a2[mb], acc[nb][mb], 0, 0, 0); }
;     }
.LBB0_1169:
	s_ashr_i32 s53, s52, 31
	s_lshl_b64 s[46:47], s[52:53], 1
	v_lshl_add_u64 v[106:107], v[78:79], 0, s[46:47]
	v_lshl_add_u64 v[118:119], v[80:81], 0, s[46:47]
	v_lshl_add_u64 v[110:111], v[76:77], 0, s[46:47]
	global_load_dwordx4 v[152:155], v[106:107], off
	global_load_dwordx4 v[156:159], v[110:111], off
	s_nop 0
	global_load_dwordx4 v[160:163], v[106:107], off offset:512
	s_nop 0
	global_load_dwordx4 v[164:167], v[110:111], off offset:512
	s_nop 0
	global_load_dwordx4 v[168:171], v[118:119], off
	s_nop 0
	global_load_dwordx4 v[172:175], v[118:119], off offset:512
	v_lshl_add_u64 v[122:123], v[2:3], 0, s[46:47]
	v_lshl_add_u64 v[126:127], v[82:83], 0, s[46:47]
	v_lshl_add_u64 v[130:131], v[84:85], 0, s[46:47]
	v_lshl_add_u64 v[134:135], v[86:87], 0, s[46:47]
	v_lshl_add_u64 v[138:139], v[88:89], 0, s[46:47]
	v_lshl_add_u64 v[142:143], v[90:91], 0, s[46:47]
	v_lshl_add_u64 v[150:151], v[92:93], 0, s[46:47]
	s_mov_b32 s46, s0
	s_add_i32 s0, s0, 16
	s_addk_i32 s52, 0x200
	s_cmp_lt_i32 s46, 8
	global_load_dwordx4 v[194:197], v[122:123], off
	s_nop 0
	global_load_dwordx4 v[198:201], v[122:123], off offset:512
	global_load_dwordx4 v[202:205], v[126:127], off
	s_nop 0
	global_load_dwordx4 v[206:209], v[126:127], off offset:512
	global_load_dwordx4 v[210:213], v[130:131], off
	s_nop 0
	global_load_dwordx4 v[214:217], v[130:131], off offset:512
	global_load_dwordx4 v[218:221], v[134:135], off
	s_nop 0
	global_load_dwordx4 v[222:225], v[134:135], off offset:512
	global_load_dwordx4 v[232:235], v[138:139], off
	s_nop 0
	global_load_dwordx4 v[240:243], v[138:139], off offset:512
	global_load_dwordx4 v[248:251], v[142:143], off
	s_nop 0
	global_load_dwordx4 v[98:101], v[142:143], off offset:512
	s_nop 0
	global_load_dwordx4 v[102:105], v[150:151], off
	global_load_dwordx4 v[114:117], v[150:151], off offset:512
	s_waitcnt vmcnt(0)
	v_mfma_f32_16x16x32_bf16 v[40:43], v[152:155], v[156:159], v[40:43]
	v_mfma_f32_16x16x32_bf16 v[64:67], v[168:171], v[156:159], v[64:67]
	v_mfma_f32_16x16x32_bf16 v[40:43], v[160:163], v[164:167], v[40:43]
	v_mfma_f32_16x16x32_bf16 v[64:67], v[172:175], v[164:167], v[64:67]
	v_mfma_f32_16x16x32_bf16 v[36:39], v[152:155], v[194:197], v[36:39]
	v_mfma_f32_16x16x32_bf16 v[60:63], v[168:171], v[194:197], v[60:63]
	v_mfma_f32_16x16x32_bf16 v[36:39], v[160:163], v[198:201], v[36:39]
	v_mfma_f32_16x16x32_bf16 v[60:63], v[172:175], v[198:201], v[60:63]
	v_mfma_f32_16x16x32_bf16 v[24:27], v[152:155], v[202:205], v[24:27]
	v_mfma_f32_16x16x32_bf16 v[56:59], v[168:171], v[202:205], v[56:59]
	v_mfma_f32_16x16x32_bf16 v[24:27], v[160:163], v[206:209], v[24:27]
	v_mfma_f32_16x16x32_bf16 v[56:59], v[172:175], v[206:209], v[56:59]
	v_mfma_f32_16x16x32_bf16 v[20:23], v[152:155], v[210:213], v[20:23]
	v_mfma_f32_16x16x32_bf16 v[52:55], v[168:171], v[210:213], v[52:55]
	v_mfma_f32_16x16x32_bf16 v[20:23], v[160:163], v[214:217], v[20:23]
	v_mfma_f32_16x16x32_bf16 v[52:55], v[172:175], v[214:217], v[52:55]
	v_mfma_f32_16x16x32_bf16 v[16:19], v[152:155], v[218:221], v[16:19]
	v_mfma_f32_16x16x32_bf16 v[48:51], v[168:171], v[218:221], v[48:51]
	v_mfma_f32_16x16x32_bf16 v[16:19], v[160:163], v[222:225], v[16:19]
	v_mfma_f32_16x16x32_bf16 v[48:51], v[172:175], v[222:225], v[48:51]
	v_mfma_f32_16x16x32_bf16 v[12:15], v[152:155], v[232:235], v[12:15]
	v_mfma_f32_16x16x32_bf16 v[44:47], v[168:171], v[232:235], v[44:47]
	v_mfma_f32_16x16x32_bf16 v[12:15], v[160:163], v[240:243], v[12:15]
	v_mfma_f32_16x16x32_bf16 v[44:47], v[172:175], v[240:243], v[44:47]
	v_mfma_f32_16x16x32_bf16 v[8:11], v[152:155], v[248:251], v[8:11]
	v_mfma_f32_16x16x32_bf16 v[28:31], v[168:171], v[248:251], v[28:31]
	v_mfma_f32_16x16x32_bf16 v[4:7], v[152:155], v[102:105], v[4:7]
	v_mfma_f32_16x16x32_bf16 v[32:35], v[168:171], v[102:105], v[32:35]
	v_mfma_f32_16x16x32_bf16 v[8:11], v[160:163], v[98:101], v[8:11]
	v_mfma_f32_16x16x32_bf16 v[28:31], v[172:175], v[98:101], v[28:31]
	v_mfma_f32_16x16x32_bf16 v[4:7], v[160:163], v[114:117], v[4:7]
	v_mfma_f32_16x16x32_bf16 v[32:35], v[172:175], v[114:117], v[32:35]
	s_cbranch_scc1 .LBB0_1169

; template <int NB>
; __device__ __forceinline__ void small_core(LAS unsigned char* lds, const bf16_t* A, int lda, const bf16_t* B0, const bf16_t* B1, int K, f32x4 (&out)[NB]) {
;     ...
;     for (; st + 8 < nsteps; st += 16) {
;         const int k = st * 32, k2 = k + 256;
;         bf16x8 b[NB], b2[NB]; b[0] = *(const bf16x8*)(bp0 + k); b2[0] = *(const bf16x8*)(bp0 + k2);
;         if (NB == 2) { b[NB - 1] = *(const bf16x8*)(bp1 + k); b2[NB - 1] = *(const bf16x8*)(bp1 + k2); }
;         bf16x8 a[8], a2[8];
; #pragma unroll
;         for (int mb = 0; mb < 8; ++mb) { a[mb] = *(const bf16x8*)(ap + (size_t)(16 * mb) * lda + k); a2[mb] = *(const bf16x8*)(ap + (size_t)(16 * mb) * lda + k2); }
; #pragma unroll
;         for (int mb = 0; mb < 8; ++mb)
; #pragma unroll
;             for (int nb = 0; nb < NB; ++nb) { acc[nb][mb] = __builtin_amdgcn_mfma_f32_16x16x32_bf16(b[nb], a[mb], acc[nb][mb], 0, 0, 0);
;                 acc[nb][mb] = __builtin_amdgcn_mfma_f32_16x16x32_bf16(b2[nb], a2[mb], acc[nb][mb], 0, 0, 0); }
;     }
;     if (st < nsteps) {
;         const int k = st * 32;
;         bf16x8 b[NB]; b[0] = *(const bf16x8*)(bp0 + k); if (NB == 2) b[NB - 1] = *(const bf16x8*)(bp1 + k);
;         bf16x8 a[8];
; #pragma unroll
;         for (int mb = 0; mb < 8; ++mb) a[mb] = *(const bf16x8*)(ap + (size_t)(16 * mb) * lda + k);
; #pragma unroll
;         for (int mb = 0; mb < 8; ++mb)
; #pragma unroll
;             for (int nb = 0; nb < NB; ++nb) acc[nb][mb] = __builtin_amdgcn_mfma_f32_16x16x32_bf16(b[nb], a[mb], acc[nb][mb], 0, 0, 0);
;     }
.LBB0_1353:
	s_ashr_i32 s39, s38, 31
	s_lshl_b64 s[40:41], s[38:39], 1
	v_lshl_add_u64 v[102:103], v[48:49], 0, s[40:41]
	v_lshl_add_u64 v[110:111], v[46:47], 0, s[40:41]
	v_lshl_add_u64 v[114:115], v[50:51], 0, s[40:41]
	v_lshl_add_u64 v[116:117], v[52:53], 0, s[40:41]
	v_lshl_add_u64 v[118:119], v[54:55], 0, s[40:41]
	v_lshl_add_u64 v[120:121], v[56:57], 0, s[40:41]
	v_lshl_add_u64 v[122:123], v[58:59], 0, s[40:41]
	v_lshl_add_u64 v[124:125], v[60:61], 0, s[40:41]
	v_lshl_add_u64 v[126:127], v[62:63], 0, s[40:41]
	global_load_dwordx4 v[128:131], v[102:103], off
	global_load_dwordx4 v[142:145], v[110:111], off
	global_load_dwordx4 v[146:149], v[114:115], off
	global_load_dwordx4 v[150:153], v[116:117], off
	global_load_dwordx4 v[154:157], v[118:119], off
	global_load_dwordx4 v[158:161], v[120:121], off
	global_load_dwordx4 v[162:165], v[122:123], off
	global_load_dwordx4 v[166:169], v[124:125], off
	s_nop 0
	global_load_dwordx4 v[170:173], v[102:103], off offset:512
	s_nop 0
	global_load_dwordx4 v[194:197], v[126:127], off
	s_nop 0
	global_load_dwordx4 v[198:201], v[110:111], off offset:512
	s_mov_b32 s37, s34
	s_add_i32 s34, s34, 16
	s_addk_i32 s38, 0x200
	s_cmp_lt_i32 s37, 8
	global_load_dwordx4 v[202:205], v[114:115], off offset:512
	global_load_dwordx4 v[206:209], v[116:117], off offset:512
	global_load_dwordx4 v[210:213], v[118:119], off offset:512
	global_load_dwordx4 v[214:217], v[120:121], off offset:512
	global_load_dwordx4 v[218:221], v[122:123], off offset:512
	global_load_dwordx4 v[222:225], v[124:125], off offset:512
	global_load_dwordx4 v[232:235], v[126:127], off offset:512
	s_waitcnt vmcnt(0)
	v_mfma_f32_16x16x32_bf16 v[28:31], v[128:131], v[142:145], v[28:31]
	v_mfma_f32_16x16x32_bf16 v[24:27], v[128:131], v[146:149], v[24:27]
	v_mfma_f32_16x16x32_bf16 v[20:23], v[128:131], v[150:153], v[20:23]
	v_mfma_f32_16x16x32_bf16 v[16:19], v[128:131], v[154:157], v[16:19]
	v_mfma_f32_16x16x32_bf16 v[12:15], v[128:131], v[158:161], v[12:15]
	v_mfma_f32_16x16x32_bf16 v[8:11], v[128:131], v[162:165], v[8:11]
	v_mfma_f32_16x16x32_bf16 v[4:7], v[128:131], v[166:169], v[4:7]
	v_mfma_f32_16x16x32_bf16 v[0:3], v[128:131], v[194:197], v[0:3]
	v_mfma_f32_16x16x32_bf16 v[28:31], v[170:173], v[198:201], v[28:31]
	v_mfma_f32_16x16x32_bf16 v[24:27], v[170:173], v[202:205], v[24:27]
	v_mfma_f32_16x16x32_bf16 v[20:23], v[170:173], v[206:209], v[20:23]
	v_mfma_f32_16x16x32_bf16 v[16:19], v[170:173], v[210:213], v[16:19]
	v_mfma_f32_16x16x32_bf16 v[12:15], v[170:173], v[214:217], v[12:15]
	v_mfma_f32_16x16x32_bf16 v[8:11], v[170:173], v[218:221], v[8:11]
	v_mfma_f32_16x16x32_bf16 v[4:7], v[170:173], v[222:225], v[4:7]
	v_mfma_f32_16x16x32_bf16 v[0:3], v[170:173], v[232:235], v[0:3]
	s_cbranch_scc1 .LBB0_1353
.LBB0_1354:
	s_cmp_gt_u32 s34, 31
	s_cbranch_scc1 .LBB0_1356
	s_lshl_b32 s34, s34, 6
	v_lshl_add_u64 v[48:49], v[48:49], 0, s[34:35]
	global_load_dwordx4 v[128:131], v[48:49], off
	v_lshl_add_u64 v[46:47], v[46:47], 0, s[34:35]
	global_load_dwordx4 v[142:145], v[46:47], off
	v_add_co_u32_e32 v56, vcc, 0x8000, v46
	v_addc_co_u32_e32 v57, vcc, 0, v47, vcc
	v_add_co_u32_e32 v60, vcc, 0x10000, v46
	s_nop 1
	v_addc_co_u32_e32 v61, vcc, 0, v47, vcc
	v_add_co_u32_e32 v70, vcc, 0x18000, v46
	global_load_dwordx4 v[146:149], v[56:57], off
	s_nop 0
	global_load_dwordx4 v[150:153], v[60:61], off
	v_addc_co_u32_e32 v71, vcc, 0, v47, vcc
	v_add_co_u32_e32 v74, vcc, 0x20000, v46
	v_addc_co_u32_e32 v75, vcc, 0, v47, vcc
	global_load_dwordx4 v[154:157], v[74:75], off
	v_add_co_u32_e32 v74, vcc, 0x28000, v46
	s_nop 0
	v_addc_co_u32_e32 v75, vcc, 0, v47, vcc
	v_add_co_u32_e32 v60, vcc, 0x30000, v46
	global_load_dwordx4 v[158:161], v[74:75], off
	s_nop 0
	v_addc_co_u32_e32 v61, vcc, 0, v47, vcc
	global_load_dwordx4 v[162:165], v[60:61], off
	v_add_co_u32_e32 v46, vcc, 0x38000, v46
	global_load_dwordx4 v[166:169], v[70:71], off
	s_nop 0
	v_addc_co_u32_e32 v47, vcc, 0, v47, vcc
	global_load_dwordx4 v[170:173], v[46:47], off
	s_waitcnt vmcnt(0)
	v_mfma_f32_16x16x32_bf16 v[28:31], v[128:131], v[142:145], v[28:31]
	v_mfma_f32_16x16x32_bf16 v[20:23], v[128:131], v[150:153], v[20:23]
	v_mfma_f32_16x16x32_bf16 v[24:27], v[128:131], v[146:149], v[24:27]
	v_mfma_f32_16x16x32_bf16 v[12:15], v[128:131], v[154:157], v[12:15]
	v_mfma_f32_16x16x32_bf16 v[4:7], v[128:131], v[162:165], v[4:7]
	v_mfma_f32_16x16x32_bf16 v[16:19], v[128:131], v[166:169], v[16:19]
	v_mfma_f32_16x16x32_bf16 v[8:11], v[128:131], v[158:161], v[8:11]
	v_mfma_f32_16x16x32_bf16 v[0:3], v[128:131], v[170:173], v[0:3]

; template <int NB>
; __device__ __forceinline__ void small_core(LAS unsigned char* lds, const bf16_t* A, int lda, const bf16_t* B0, const bf16_t* B1, int K, f32x4 (&out)[NB]) {
;     ...
;     for (; st + 8 < nsteps; st += 16) {
;         const int k = st * 32, k2 = k + 256;
;         bf16x8 b[NB], b2[NB]; b[0] = *(const bf16x8*)(bp0 + k); b2[0] = *(const bf16x8*)(bp0 + k2);
;         if (NB == 2) { b[NB - 1] = *(const bf16x8*)(bp1 + k); b2[NB - 1] = *(const bf16x8*)(bp1 + k2); }
;         bf16x8 a[8], a2[8];
; #pragma unroll
;         for (int mb = 0; mb < 8; ++mb) { a[mb] = *(const bf16x8*)(ap + (size_t)(16 * mb) * lda + k); a2[mb] = *(const bf16x8*)(ap + (size_t)(16 * mb) * lda + k2); }
; #pragma unroll
;         for (int mb = 0; mb < 8; ++mb)
; #pragma unroll
;             for (int nb = 0; nb < NB; ++nb) { acc[nb][mb] = __builtin_amdgcn_mfma_f32_16x16x32_bf16(b[nb], a[mb], acc[nb][mb], 0, 0, 0);
;                 acc[nb][mb] = __builtin_amdgcn_mfma_f32_16x16x32_bf16(b2[nb], a2[mb], acc[nb][mb], 0, 0, 0); }
;     }
;     if (st < nsteps) {
;         const int k = st * 32;
;         bf16x8 b[NB]; b[0] = *(const bf16x8*)(bp0 + k); if (NB == 2) b[NB - 1] = *(const bf16x8*)(bp1 + k);
;         bf16x8 a[8];
; #pragma unroll
;         for (int mb = 0; mb < 8; ++mb) a[mb] = *(const bf16x8*)(ap + (size_t)(16 * mb) * lda + k);
; #pragma unroll
;         for (int mb = 0; mb < 8; ++mb)
; #pragma unroll
;             for (int nb = 0; nb < NB; ++nb) acc[nb][mb] = __builtin_amdgcn_mfma_f32_16x16x32_bf16(b[nb], a[mb], acc[nb][mb], 0, 0, 0);
;     }
.LBB0_1606:
	s_ashr_i32 s53, s52, 31
	s_lshl_b64 s[46:47], s[52:53], 1
	v_lshl_add_u64 v[98:99], v[48:49], 0, s[46:47]
	v_lshl_add_u64 v[106:107], v[46:47], 0, s[46:47]
	v_lshl_add_u64 v[110:111], v[50:51], 0, s[46:47]
	v_lshl_add_u64 v[112:113], v[52:53], 0, s[46:47]
	v_lshl_add_u64 v[114:115], v[54:55], 0, s[46:47]
	v_lshl_add_u64 v[116:117], v[56:57], 0, s[46:47]
	v_lshl_add_u64 v[118:119], v[58:59], 0, s[46:47]
	v_lshl_add_u64 v[120:121], v[60:61], 0, s[46:47]
	v_lshl_add_u64 v[122:123], v[62:63], 0, s[46:47]
	global_load_dwordx4 v[124:127], v[98:99], off
	global_load_dwordx4 v[128:131], v[106:107], off
	global_load_dwordx4 v[132:135], v[110:111], off
	global_load_dwordx4 v[136:139], v[112:113], off
	global_load_dwordx4 v[140:143], v[114:115], off
	global_load_dwordx4 v[144:147], v[116:117], off
	global_load_dwordx4 v[148:151], v[118:119], off
	global_load_dwordx4 v[152:155], v[120:121], off
	s_nop 0
	global_load_dwordx4 v[156:159], v[98:99], off offset:512
	s_nop 0
	global_load_dwordx4 v[160:163], v[122:123], off
	s_nop 0
	global_load_dwordx4 v[164:167], v[106:107], off offset:512
	s_mov_b32 s33, s12
	s_add_i32 s12, s12, 16
	s_addk_i32 s52, 0x200
	s_cmp_lt_i32 s33, 8
	global_load_dwordx4 v[168:171], v[110:111], off offset:512
	global_load_dwordx4 v[172:175], v[112:113], off offset:512
	global_load_dwordx4 v[184:187], v[114:115], off offset:512
	global_load_dwordx4 v[188:191], v[116:117], off offset:512
	global_load_dwordx4 v[192:195], v[118:119], off offset:512
	global_load_dwordx4 v[196:199], v[120:121], off offset:512
	global_load_dwordx4 v[200:203], v[122:123], off offset:512
	s_waitcnt vmcnt(0)
	v_mfma_f32_16x16x32_bf16 v[28:31], v[124:127], v[128:131], v[28:31]
	v_mfma_f32_16x16x32_bf16 v[24:27], v[124:127], v[132:135], v[24:27]
	v_mfma_f32_16x16x32_bf16 v[20:23], v[124:127], v[136:139], v[20:23]
	v_mfma_f32_16x16x32_bf16 v[16:19], v[124:127], v[140:143], v[16:19]
	v_mfma_f32_16x16x32_bf16 v[12:15], v[124:127], v[144:147], v[12:15]
	v_mfma_f32_16x16x32_bf16 v[8:11], v[124:127], v[148:151], v[8:11]
	v_mfma_f32_16x16x32_bf16 v[4:7], v[124:127], v[152:155], v[4:7]
	v_mfma_f32_16x16x32_bf16 v[0:3], v[124:127], v[160:163], v[0:3]
	v_mfma_f32_16x16x32_bf16 v[28:31], v[156:159], v[164:167], v[28:31]
	v_mfma_f32_16x16x32_bf16 v[24:27], v[156:159], v[168:171], v[24:27]
	v_mfma_f32_16x16x32_bf16 v[20:23], v[156:159], v[172:175], v[20:23]
	v_mfma_f32_16x16x32_bf16 v[16:19], v[156:159], v[184:187], v[16:19]
	v_mfma_f32_16x16x32_bf16 v[12:15], v[156:159], v[188:191], v[12:15]
	v_mfma_f32_16x16x32_bf16 v[8:11], v[156:159], v[192:195], v[8:11]
	v_mfma_f32_16x16x32_bf16 v[4:7], v[156:159], v[196:199], v[4:7]
	v_mfma_f32_16x16x32_bf16 v[0:3], v[156:159], v[200:203], v[0:3]
	s_cbranch_scc1 .LBB0_1606
.LBB0_1607:
	s_cmp_gt_u32 s12, 31
	s_cbranch_scc1 .LBB0_1609
	s_lshl_b32 s12, s12, 6
	v_lshl_add_u64 v[48:49], v[48:49], 0, s[12:13]
	global_load_dwordx4 v[124:127], v[48:49], off
	v_lshl_add_u64 v[46:47], v[46:47], 0, s[12:13]
	global_load_dwordx4 v[128:131], v[46:47], off
	v_add_co_u32_e32 v56, vcc, 0x8000, v46
	v_addc_co_u32_e32 v57, vcc, 0, v47, vcc
	v_add_co_u32_e32 v60, vcc, 0x10000, v46
	s_nop 1
	v_addc_co_u32_e32 v61, vcc, 0, v47, vcc
	v_add_co_u32_e32 v66, vcc, 0x18000, v46
	global_load_dwordx4 v[132:135], v[56:57], off
	s_nop 0
	global_load_dwordx4 v[136:139], v[60:61], off
	v_addc_co_u32_e32 v67, vcc, 0, v47, vcc
	v_add_co_u32_e32 v70, vcc, 0x20000, v46
	v_addc_co_u32_e32 v71, vcc, 0, v47, vcc
	global_load_dwordx4 v[140:143], v[70:71], off
	v_add_co_u32_e32 v70, vcc, 0x28000, v46
	s_nop 0
	v_addc_co_u32_e32 v71, vcc, 0, v47, vcc
	v_add_co_u32_e32 v60, vcc, 0x30000, v46
	global_load_dwordx4 v[144:147], v[70:71], off
	s_nop 0
	v_addc_co_u32_e32 v61, vcc, 0, v47, vcc
	global_load_dwordx4 v[148:151], v[60:61], off
	v_add_co_u32_e32 v46, vcc, 0x38000, v46
	global_load_dwordx4 v[152:155], v[66:67], off
	s_nop 0
	v_addc_co_u32_e32 v47, vcc, 0, v47, vcc
	global_load_dwordx4 v[156:159], v[46:47], off
	s_waitcnt vmcnt(0)
	v_mfma_f32_16x16x32_bf16 v[28:31], v[124:127], v[128:131], v[28:31]
	v_mfma_f32_16x16x32_bf16 v[20:23], v[124:127], v[136:139], v[20:23]
	v_mfma_f32_16x16x32_bf16 v[24:27], v[124:127], v[132:135], v[24:27]
	v_mfma_f32_16x16x32_bf16 v[12:15], v[124:127], v[140:143], v[12:15]
	v_mfma_f32_16x16x32_bf16 v[4:7], v[124:127], v[148:151], v[4:7]
	v_mfma_f32_16x16x32_bf16 v[16:19], v[124:127], v[152:155], v[16:19]
	v_mfma_f32_16x16x32_bf16 v[8:11], v[124:127], v[144:147], v[8:11]
	v_mfma_f32_16x16x32_bf16 v[0:3], v[124:127], v[156:159], v[0:3]

; template <int NB>
; __device__ __forceinline__ void small_core(LAS unsigned char* lds, const bf16_t* A, int lda, const bf16_t* B0, const bf16_t* B1, int K, f32x4 (&out)[NB]) {
;     ...
;     for (; st + 8 < nsteps; st += 16) {
;         const int k = st * 32, k2 = k + 256;
;         bf16x8 b[NB], b2[NB]; b[0] = *(const bf16x8*)(bp0 + k); b2[0] = *(const bf16x8*)(bp0 + k2);
;         if (NB == 2) { b[NB - 1] = *(const bf16x8*)(bp1 + k); b2[NB - 1] = *(const bf16x8*)(bp1 + k2); }
;         bf16x8 a[8], a2[8];
; #pragma unroll
;         for (int mb = 0; mb < 8; ++mb) { a[mb] = *(const bf16x8*)(ap + (size_t)(16 * mb) * lda + k); a2[mb] = *(const bf16x8*)(ap + (size_t)(16 * mb) * lda + k2); }
; #pragma unroll
;         for (int mb = 0; mb < 8; ++mb)
; #pragma unroll
;             for (int nb = 0; nb < NB; ++nb) { acc[nb][mb] = __builtin_amdgcn_mfma_f32_16x16x32_bf16(b[nb], a[mb], acc[nb][mb], 0, 0, 0);
;                 acc[nb][mb] = __builtin_amdgcn_mfma_f32_16x16x32_bf16(b2[nb], a2[mb], acc[nb][mb], 0, 0, 0); }
;     }
.LBB0_1710:
	s_ashr_i32 s35, s34, 31
	s_lshl_b64 s[36:37], s[34:35], 1
	v_lshl_add_u64 v[106:107], v[78:79], 0, s[36:37]
	v_lshl_add_u64 v[118:119], v[80:81], 0, s[36:37]
	v_lshl_add_u64 v[110:111], v[76:77], 0, s[36:37]
	global_load_dwordx4 v[152:155], v[106:107], off
	global_load_dwordx4 v[156:159], v[110:111], off
	s_nop 0
	global_load_dwordx4 v[160:163], v[106:107], off offset:512
	s_nop 0
	global_load_dwordx4 v[164:167], v[110:111], off offset:512
	s_nop 0
	global_load_dwordx4 v[168:171], v[118:119], off
	s_nop 0
	global_load_dwordx4 v[172:175], v[118:119], off offset:512
	v_lshl_add_u64 v[122:123], v[2:3], 0, s[36:37]
	v_lshl_add_u64 v[126:127], v[82:83], 0, s[36:37]
	v_lshl_add_u64 v[130:131], v[84:85], 0, s[36:37]
	v_lshl_add_u64 v[134:135], v[86:87], 0, s[36:37]
	v_lshl_add_u64 v[138:139], v[88:89], 0, s[36:37]
	v_lshl_add_u64 v[142:143], v[90:91], 0, s[36:37]
	v_lshl_add_u64 v[150:151], v[92:93], 0, s[36:37]
	s_mov_b32 s35, s0
	s_add_i32 s0, s0, 16
	s_addk_i32 s34, 0x200
	s_cmp_lt_i32 s35, 8
	global_load_dwordx4 v[184:187], v[122:123], off
	s_nop 0
	global_load_dwordx4 v[188:191], v[122:123], off offset:512
	global_load_dwordx4 v[192:195], v[126:127], off
	s_nop 0
	global_load_dwordx4 v[196:199], v[126:127], off offset:512
	global_load_dwordx4 v[200:203], v[130:131], off
	s_nop 0
	global_load_dwordx4 v[204:207], v[130:131], off offset:512
	global_load_dwordx4 v[208:211], v[134:135], off
	s_nop 0
	global_load_dwordx4 v[212:215], v[134:135], off offset:512
	global_load_dwordx4 v[216:219], v[138:139], off
	s_nop 0
	global_load_dwordx4 v[220:223], v[138:139], off offset:512
	global_load_dwordx4 v[230:233], v[142:143], off
	s_nop 0
	global_load_dwordx4 v[234:237], v[142:143], off offset:512
	s_nop 0
	global_load_dwordx4 v[240:243], v[150:151], off
	global_load_dwordx4 v[246:249], v[150:151], off offset:512
	s_waitcnt vmcnt(0)
	v_mfma_f32_16x16x32_bf16 v[40:43], v[152:155], v[156:159], v[40:43]
	v_mfma_f32_16x16x32_bf16 v[64:67], v[168:171], v[156:159], v[64:67]
	v_mfma_f32_16x16x32_bf16 v[40:43], v[160:163], v[164:167], v[40:43]
	v_mfma_f32_16x16x32_bf16 v[64:67], v[172:175], v[164:167], v[64:67]
	v_mfma_f32_16x16x32_bf16 v[36:39], v[152:155], v[184:187], v[36:39]
	v_mfma_f32_16x16x32_bf16 v[60:63], v[168:171], v[184:187], v[60:63]
	v_mfma_f32_16x16x32_bf16 v[36:39], v[160:163], v[188:191], v[36:39]
	v_mfma_f32_16x16x32_bf16 v[60:63], v[172:175], v[188:191], v[60:63]
	v_mfma_f32_16x16x32_bf16 v[24:27], v[152:155], v[192:195], v[24:27]
	v_mfma_f32_16x16x32_bf16 v[56:59], v[168:171], v[192:195], v[56:59]
	v_mfma_f32_16x16x32_bf16 v[24:27], v[160:163], v[196:199], v[24:27]
	v_mfma_f32_16x16x32_bf16 v[56:59], v[172:175], v[196:199], v[56:59]
	v_mfma_f32_16x16x32_bf16 v[20:23], v[152:155], v[200:203], v[20:23]
	v_mfma_f32_16x16x32_bf16 v[52:55], v[168:171], v[200:203], v[52:55]
	v_mfma_f32_16x16x32_bf16 v[20:23], v[160:163], v[204:207], v[20:23]
	v_mfma_f32_16x16x32_bf16 v[52:55], v[172:175], v[204:207], v[52:55]
	v_mfma_f32_16x16x32_bf16 v[16:19], v[152:155], v[208:211], v[16:19]
	v_mfma_f32_16x16x32_bf16 v[48:51], v[168:171], v[208:211], v[48:51]
	v_mfma_f32_16x16x32_bf16 v[16:19], v[160:163], v[212:215], v[16:19]
	v_mfma_f32_16x16x32_bf16 v[48:51], v[172:175], v[212:215], v[48:51]
	v_mfma_f32_16x16x32_bf16 v[12:15], v[152:155], v[216:219], v[12:15]
	v_mfma_f32_16x16x32_bf16 v[44:47], v[168:171], v[216:219], v[44:47]
	v_mfma_f32_16x16x32_bf16 v[12:15], v[160:163], v[220:223], v[12:15]
	v_mfma_f32_16x16x32_bf16 v[44:47], v[172:175], v[220:223], v[44:47]
	v_mfma_f32_16x16x32_bf16 v[8:11], v[152:155], v[230:233], v[8:11]
	v_mfma_f32_16x16x32_bf16 v[28:31], v[168:171], v[230:233], v[28:31]
	v_mfma_f32_16x16x32_bf16 v[4:7], v[152:155], v[240:243], v[4:7]
	v_mfma_f32_16x16x32_bf16 v[32:35], v[168:171], v[240:243], v[32:35]
	v_mfma_f32_16x16x32_bf16 v[8:11], v[160:163], v[234:237], v[8:11]
	v_mfma_f32_16x16x32_bf16 v[28:31], v[172:175], v[234:237], v[28:31]
	v_mfma_f32_16x16x32_bf16 v[4:7], v[160:163], v[246:249], v[4:7]
	v_mfma_f32_16x16x32_bf16 v[32:35], v[172:175], v[246:249], v[32:35]
	s_cbranch_scc1 .LBB0_1710

; template <int NB>
; __device__ __forceinline__ void small_core(LAS unsigned char* lds, const bf16_t* A, int lda, const bf16_t* B0, const bf16_t* B1, int K, f32x4 (&out)[NB]) {
;     ...
;     for (; st + 8 < nsteps; st += 16) {
;         const int k = st * 32, k2 = k + 256;
;         bf16x8 b[NB], b2[NB]; b[0] = *(const bf16x8*)(bp0 + k); b2[0] = *(const bf16x8*)(bp0 + k2);
;         if (NB == 2) { b[NB - 1] = *(const bf16x8*)(bp1 + k); b2[NB - 1] = *(const bf16x8*)(bp1 + k2); }
;         bf16x8 a[8], a2[8];
; #pragma unroll
;         for (int mb = 0; mb < 8; ++mb) { a[mb] = *(const bf16x8*)(ap + (size_t)(16 * mb) * lda + k); a2[mb] = *(const bf16x8*)(ap + (size_t)(16 * mb) * lda + k2); }
; #pragma unroll
;         for (int mb = 0; mb < 8; ++mb)
; #pragma unroll
;             for (int nb = 0; nb < NB; ++nb) { acc[nb][mb] = __builtin_amdgcn_mfma_f32_16x16x32_bf16(b[nb], a[mb], acc[nb][mb], 0, 0, 0);
;                 acc[nb][mb] = __builtin_amdgcn_mfma_f32_16x16x32_bf16(b2[nb], a2[mb], acc[nb][mb], 0, 0, 0); }
;     }
;     if (st < nsteps) {
;         const int k = st * 32;
;         bf16x8 b[NB]; b[0] = *(const bf16x8*)(bp0 + k); if (NB == 2) b[NB - 1] = *(const bf16x8*)(bp1 + k);
;         bf16x8 a[8];
; #pragma unroll
;         for (int mb = 0; mb < 8; ++mb) a[mb] = *(const bf16x8*)(ap + (size_t)(16 * mb) * lda + k);
; #pragma unroll
;         for (int mb = 0; mb < 8; ++mb)
; #pragma unroll
;             for (int nb = 0; nb < NB; ++nb) acc[nb][mb] = __builtin_amdgcn_mfma_f32_16x16x32_bf16(b[nb], a[mb], acc[nb][mb], 0, 0, 0);
;     }
.LBB0_1786:
	s_ashr_i32 s29, s28, 31
	s_lshl_b64 s[34:35], s[28:29], 1
	v_lshl_add_u64 v[98:99], v[48:49], 0, s[34:35]
	v_lshl_add_u64 v[106:107], v[46:47], 0, s[34:35]
	v_lshl_add_u64 v[110:111], v[50:51], 0, s[34:35]
	v_lshl_add_u64 v[112:113], v[52:53], 0, s[34:35]
	v_lshl_add_u64 v[114:115], v[54:55], 0, s[34:35]
	v_lshl_add_u64 v[116:117], v[56:57], 0, s[34:35]
	v_lshl_add_u64 v[118:119], v[58:59], 0, s[34:35]
	v_lshl_add_u64 v[120:121], v[60:61], 0, s[34:35]
	v_lshl_add_u64 v[122:123], v[62:63], 0, s[34:35]
	global_load_dwordx4 v[124:127], v[98:99], off
	global_load_dwordx4 v[128:131], v[106:107], off
	global_load_dwordx4 v[132:135], v[110:111], off
	global_load_dwordx4 v[136:139], v[112:113], off
	global_load_dwordx4 v[140:143], v[114:115], off
	global_load_dwordx4 v[144:147], v[116:117], off
	global_load_dwordx4 v[148:151], v[118:119], off
	global_load_dwordx4 v[152:155], v[120:121], off
	s_nop 0
	global_load_dwordx4 v[156:159], v[98:99], off offset:512
	s_nop 0
	global_load_dwordx4 v[160:163], v[122:123], off
	s_nop 0
	global_load_dwordx4 v[164:167], v[106:107], off offset:512
	s_mov_b32 s29, s6
	s_add_i32 s6, s6, 16
	s_addk_i32 s28, 0x200
	s_cmp_lt_i32 s29, 64
	global_load_dwordx4 v[168:171], v[110:111], off offset:512
	global_load_dwordx4 v[172:175], v[112:113], off offset:512
	global_load_dwordx4 v[182:185], v[114:115], off offset:512
	global_load_dwordx4 v[186:189], v[116:117], off offset:512
	global_load_dwordx4 v[190:193], v[118:119], off offset:512
	global_load_dwordx4 v[194:197], v[120:121], off offset:512
	global_load_dwordx4 v[198:201], v[122:123], off offset:512
	s_waitcnt vmcnt(0)
	v_mfma_f32_16x16x32_bf16 v[28:31], v[124:127], v[128:131], v[28:31]
	v_mfma_f32_16x16x32_bf16 v[24:27], v[124:127], v[132:135], v[24:27]
	v_mfma_f32_16x16x32_bf16 v[20:23], v[124:127], v[136:139], v[20:23]
	v_mfma_f32_16x16x32_bf16 v[16:19], v[124:127], v[140:143], v[16:19]
	v_mfma_f32_16x16x32_bf16 v[12:15], v[124:127], v[144:147], v[12:15]
	v_mfma_f32_16x16x32_bf16 v[8:11], v[124:127], v[148:151], v[8:11]
	v_mfma_f32_16x16x32_bf16 v[4:7], v[124:127], v[152:155], v[4:7]
	v_mfma_f32_16x16x32_bf16 v[0:3], v[124:127], v[160:163], v[0:3]
	v_mfma_f32_16x16x32_bf16 v[28:31], v[156:159], v[164:167], v[28:31]
	v_mfma_f32_16x16x32_bf16 v[24:27], v[156:159], v[168:171], v[24:27]
	v_mfma_f32_16x16x32_bf16 v[20:23], v[156:159], v[172:175], v[20:23]
	v_mfma_f32_16x16x32_bf16 v[16:19], v[156:159], v[182:185], v[16:19]
	v_mfma_f32_16x16x32_bf16 v[12:15], v[156:159], v[186:189], v[12:15]
	v_mfma_f32_16x16x32_bf16 v[8:11], v[156:159], v[190:193], v[8:11]
	v_mfma_f32_16x16x32_bf16 v[4:7], v[156:159], v[194:197], v[4:7]
	v_mfma_f32_16x16x32_bf16 v[0:3], v[156:159], v[198:201], v[0:3]
	s_cbranch_scc1 .LBB0_1786
.LBB0_1787:
	s_cmpk_gt_u32 s6, 0x57
	s_cbranch_scc1 .LBB0_1789
	s_lshl_b32 s6, s6, 6
	v_lshl_add_u64 v[48:49], v[48:49], 0, s[6:7]
	global_load_dwordx4 v[124:127], v[48:49], off
	v_lshl_add_u64 v[46:47], v[46:47], 0, s[6:7]
	global_load_dwordx4 v[128:131], v[46:47], off
	v_add_co_u32_e32 v56, vcc, 0x16000, v46
	v_addc_co_u32_e32 v57, vcc, 0, v47, vcc
	v_add_co_u32_e32 v60, vcc, 0x2c000, v46
	s_nop 1
	v_addc_co_u32_e32 v61, vcc, 0, v47, vcc
	v_add_co_u32_e32 v66, vcc, 0x42000, v46
	global_load_dwordx4 v[132:135], v[56:57], off
	s_nop 0
	global_load_dwordx4 v[136:139], v[60:61], off
	v_addc_co_u32_e32 v67, vcc, 0, v47, vcc
	v_add_co_u32_e32 v70, vcc, 0x58000, v46
	v_addc_co_u32_e32 v71, vcc, 0, v47, vcc
	global_load_dwordx4 v[140:143], v[70:71], off
	v_add_co_u32_e32 v70, vcc, 0x6e000, v46
	s_nop 0
	v_addc_co_u32_e32 v71, vcc, 0, v47, vcc
	v_add_co_u32_e32 v60, vcc, 0x84000, v46
	global_load_dwordx4 v[144:147], v[70:71], off
	s_nop 0
	v_addc_co_u32_e32 v61, vcc, 0, v47, vcc
	global_load_dwordx4 v[148:151], v[60:61], off
	v_add_co_u32_e32 v46, vcc, 0x9a000, v46
	global_load_dwordx4 v[152:155], v[66:67], off
	s_nop 0
	v_addc_co_u32_e32 v47, vcc, 0, v47, vcc
	global_load_dwordx4 v[156:159], v[46:47], off
	s_waitcnt vmcnt(0)
	v_mfma_f32_16x16x32_bf16 v[28:31], v[124:127], v[128:131], v[28:31]
	v_mfma_f32_16x16x32_bf16 v[20:23], v[124:127], v[136:139], v[20:23]
	v_mfma_f32_16x16x32_bf16 v[24:27], v[124:127], v[132:135], v[24:27]
	v_mfma_f32_16x16x32_bf16 v[12:15], v[124:127], v[140:143], v[12:15]
	v_mfma_f32_16x16x32_bf16 v[4:7], v[124:127], v[148:151], v[4:7]
	v_mfma_f32_16x16x32_bf16 v[16:19], v[124:127], v[152:155], v[16:19]
	v_mfma_f32_16x16x32_bf16 v[8:11], v[124:127], v[144:147], v[8:11]
	v_mfma_f32_16x16x32_bf16 v[0:3], v[124:127], v[156:159], v[0:3]
